# v083 plus the SWA in-projection GEMM epilogue in registers (rope rotation on transposed accumulators, float4 cos/sin reads one row group ahead)
# baseline (speedup 1.0000x reference)
.Lswa_epi_latch:
	s_cbranch_vccnz .LBB0_142

; #define STAGE_B(P, br, kt) do { const char* _gb = (const char*)(Bt + ((long)(br) * K + (long)(kt) * BK)); \
;     __builtin_amdgcn_global_load_lds((const unsigned*)(_gb + bofl0), (unsigned*)((char*)(P) + gtid_ * 16), 16, 0, 0); \
;     __builtin_amdgcn_global_load_lds((const unsigned*)(_gb + (long)K * 128 + bofl0), (unsigned*)((char*)(P) + gtid_ * 16 + 8192), 16, 0, 0); } while (0)
; #define LDA(dst, b, h) for (int m = 0; m < 4; ++m) for (int k = 0; k < 2; ++k) \
;     dst[m][k] = *reinterpret_cast<const bf16x8*>((char*)SA(b, h) + lds_byte(wr * 64 + m * 16 + fr, k * 32 + fq * 8))
; #define LDB(dst, b, h) for (int n = 0; n < 2; ++n) for (int k = 0; k < 2; ++k) \
;     dst[n][k] = *reinterpret_cast<const bf16x8*>((char*)SB(b, h) + lds_byte(wc * 32 + n * 16 + fr, k * 32 + fq * 8))
; #define MMA(ai, bj, At_, Bt_) do { __builtin_amdgcn_s_setprio(1); \
;     for (int m = 0; m < 4; ++m) for (int n = 0; n < 2; ++n) for (int k = 0; k < 2; ++k) \
;       acc[ai][bj][m][n] = __builtin_amdgcn_mfma_f32_16x16x32_bf16(At_[m][k], Bt_[n][k], acc[ai][bj][m][n], 0, 0, 0); \
;     __builtin_amdgcn_s_setprio(0); } while (0)
; #define WAIT_V(n) asm volatile("s_waitcnt vmcnt(" #n ")" ::: "memory")
; #define WAIT_L(n) asm volatile("s_waitcnt lgkmcnt(" #n ")" ::: "memory")
; #define BAR __builtin_amdgcn_s_barrier()
; #define SCHED __builtin_amdgcn_sched_barrier(0)
; template <int EPI>
; __device__ __forceinline__ void gemm_tile(const GemmArgs& g, int brow, int bcol, int parity, bool first, bool nvalid, int nbrow, int nbcol) {
;     ...
;   for (int t = 0; t < nt - 2; t += 2) {
;     LDB(B0, 0, 0); SCHED; LDA(At, 0, 0); STAGE_A(SA(1, 1), brow + HALF, t + 1);
;     WAIT_L(8); BAR; WAIT_L(0); MMA(0, 0, At, B0); BAR; SCHED;
;     LDB(B1, 0, 1); STAGE_B(SB(0, 0), bcol, t + 2);
;     BAR; WAIT_L(0); MMA(0, 1, At, B1); BAR; SCHED;
;     LDA(At, 0, 1); STAGE_A(SA(0, 0), brow, t + 2);
;     BAR; WAIT_L(0); MMA(1, 0, At, B0); BAR; SCHED;
;     STAGE_B(SB(0, 1), bcol + HALF, t + 2);
;     WAIT_V(6); BAR; MMA(1, 1, At, B1); BAR; SCHED;
;     LDB(B0, 1, 0); SCHED; LDA(At, 1, 0); STAGE_A(SA(0, 1), brow + HALF, t + 2);
;     WAIT_L(8); BAR; WAIT_L(0); MMA(0, 0, At, B0); BAR; SCHED;
.LBB0_133:
	ds_read_b128 v[164:167], v157
	ds_read_b128 v[168:171], v157 offset:1024
	ds_read_b128 v[172:175], v157 offset:2048
	ds_read_b128 v[176:179], v157 offset:3072
	ds_read_b128 v[180:183], v146
	ds_read_b128 v[184:187], v146 offset:1024
	ds_read_b128 v[188:191], v145
	ds_read_b128 v[192:195], v145 offset:1024
	ds_read_b128 v[196:199], v144
	ds_read_b128 v[202:205], v144 offset:1024
	ds_read_b128 v[206:209], v143
	ds_read_b128 v[216:219], v143 offset:1024
	s_waitcnt lgkmcnt(6)
	ds_read_b128 v[222:225], v154
	ds_read_b128 v[228:231], v154 offset:1024
	ds_read_b128 v[232:235], v154 offset:2048
	ds_read_b128 v[236:239], v154 offset:3072
	v_add_u32_e32 v161, 0xc000, v137
	v_lshl_add_u64 v[210:211], s[12:13], 0, v[130:131]
	v_readfirstlane_b32 s2, v161
	v_add_u32_e32 v162, 0xe000, v137
	v_lshl_add_u64 v[158:159], v[210:211], 0, s[24:25]
	s_mov_b32 m0, s2
	v_readfirstlane_b32 s2, v162
	global_load_lds_dwordx4 v[158:159], off
	v_lshl_add_u64 v[158:159], v[210:211], 0, s[34:35]
	s_mov_b32 m0, s2
	s_nop 0
	global_load_lds_dwordx4 v[158:159], off
	s_waitcnt vmcnt(8)
	s_barrier
	s_waitcnt lgkmcnt(0)
	v_mfma_f32_16x16x32_bf16 v[126:129], v[164:167], v[180:183], v[126:129]
	v_mfma_f32_16x16x32_bf16 v[122:125], v[172:175], v[180:183], v[122:125]
	v_mfma_f32_16x16x32_bf16 v[118:121], v[164:167], v[188:191], v[118:121]
	v_mfma_f32_16x16x32_bf16 v[114:117], v[172:175], v[188:191], v[114:117]
	v_mfma_f32_16x16x32_bf16 v[110:113], v[164:167], v[196:199], v[110:113]
	v_mfma_f32_16x16x32_bf16 v[106:109], v[172:175], v[196:199], v[106:109]
	v_mfma_f32_16x16x32_bf16 v[102:105], v[164:167], v[206:209], v[102:105]
	v_mfma_f32_16x16x32_bf16 v[98:101], v[172:175], v[206:209], v[98:101]
	v_mfma_f32_16x16x32_bf16 v[126:129], v[168:171], v[184:187], v[126:129]
	v_mfma_f32_16x16x32_bf16 v[122:125], v[176:179], v[184:187], v[122:125]
	v_mfma_f32_16x16x32_bf16 v[118:121], v[168:171], v[192:195], v[118:121]
	v_mfma_f32_16x16x32_bf16 v[114:117], v[176:179], v[192:195], v[114:117]
	v_mfma_f32_16x16x32_bf16 v[110:113], v[168:171], v[202:205], v[110:113]
	v_mfma_f32_16x16x32_bf16 v[106:109], v[176:179], v[202:205], v[106:109]
	v_mfma_f32_16x16x32_bf16 v[102:105], v[168:171], v[216:219], v[102:105]
	v_mfma_f32_16x16x32_bf16 v[98:101], v[176:179], v[216:219], v[98:101]
	v_mfma_f32_16x16x32_bf16 v[94:97], v[222:225], v[180:183], v[94:97]
	v_mfma_f32_16x16x32_bf16 v[90:93], v[232:235], v[180:183], v[90:93]
	v_mfma_f32_16x16x32_bf16 v[86:89], v[222:225], v[188:191], v[86:89]
	v_mfma_f32_16x16x32_bf16 v[82:85], v[232:235], v[188:191], v[82:85]
	v_mfma_f32_16x16x32_bf16 v[78:81], v[222:225], v[196:199], v[78:81]
	v_mfma_f32_16x16x32_bf16 v[74:77], v[232:235], v[196:199], v[74:77]
	v_mfma_f32_16x16x32_bf16 v[70:73], v[222:225], v[206:209], v[70:73]
	v_mfma_f32_16x16x32_bf16 v[66:69], v[232:235], v[206:209], v[66:69]
	v_mfma_f32_16x16x32_bf16 v[94:97], v[228:231], v[184:187], v[94:97]
	v_mfma_f32_16x16x32_bf16 v[90:93], v[236:239], v[184:187], v[90:93]
	v_mfma_f32_16x16x32_bf16 v[86:89], v[228:231], v[192:195], v[86:89]
	v_mfma_f32_16x16x32_bf16 v[82:85], v[236:239], v[192:195], v[82:85]
	v_mfma_f32_16x16x32_bf16 v[78:81], v[228:231], v[202:205], v[78:81]
	v_mfma_f32_16x16x32_bf16 v[74:77], v[236:239], v[202:205], v[74:77]
	v_mfma_f32_16x16x32_bf16 v[70:73], v[228:231], v[216:219], v[70:73]
	v_mfma_f32_16x16x32_bf16 v[66:69], v[236:239], v[216:219], v[66:69]
	s_barrier
	ds_read_b128 v[180:183], v146 offset:16384
	ds_read_b128 v[184:187], v146 offset:17408
	ds_read_b128 v[188:191], v145 offset:16384
	ds_read_b128 v[192:195], v145 offset:17408
	ds_read_b128 v[196:199], v144 offset:16384
	ds_read_b128 v[202:205], v144 offset:17408
	ds_read_b128 v[206:209], v143 offset:16384
	ds_read_b128 v[216:219], v143 offset:17408
	v_add_u32_e32 v158, s15, v141
	v_lshl_add_u64 v[212:213], s[0:1], 0, v[130:131]
	v_readfirstlane_b32 s2, v158
	v_add_u32_e32 v159, 0x2000, v158
	v_lshl_add_u64 v[240:241], v[212:213], 0, s[78:79]
	s_mov_b32 m0, s2
	v_readfirstlane_b32 s2, v159
	global_load_lds_dwordx4 v[240:241], off
	v_lshl_add_u64 v[240:241], v[212:213], 0, s[52:53]
	s_mov_b32 m0, s2
	s_nop 0
	global_load_lds_dwordx4 v[240:241], off
	v_readfirstlane_b32 s2, v137
	v_lshl_add_u64 v[240:241], v[210:211], 0, s[36:37]
	s_mov_b32 m0, s2
	v_readfirstlane_b32 s2, v136
	global_load_lds_dwordx4 v[240:241], off
	v_lshl_add_u64 v[240:241], v[210:211], 0, s[42:43]
	s_mov_b32 m0, s2
	s_nop 0
	global_load_lds_dwordx4 v[240:241], off
	v_readfirstlane_b32 s2, v135
	v_add_u32_e32 v160, 0x2000, v135
	v_lshl_add_u64 v[244:245], v[212:213], 0, s[56:57]
	s_mov_b32 m0, s2
	v_readfirstlane_b32 s2, v160
	global_load_lds_dwordx4 v[244:245], off
	v_lshl_add_u64 v[244:245], v[212:213], 0, s[66:67]
	s_mov_b32 m0, s2
	s_nop 0
	global_load_lds_dwordx4 v[244:245], off
	s_waitcnt vmcnt(8)
	s_barrier
; #define STAGE_B(P, br, kt) do { const char* _gb = (const char*)(Bt + ((long)(br) * K + (long)(kt) * BK)); \
;     __builtin_amdgcn_global_load_lds((const unsigned*)(_gb + bofl0), (unsigned*)((char*)(P) + gtid_ * 16), 16, 0, 0); \
;     __builtin_amdgcn_global_load_lds((const unsigned*)(_gb + (long)K * 128 + bofl0), (unsigned*)((char*)(P) + gtid_ * 16 + 8192), 16, 0, 0); } while (0)
; #define LDA(dst, b, h) for (int m = 0; m < 4; ++m) for (int k = 0; k < 2; ++k) \
;     dst[m][k] = *reinterpret_cast<const bf16x8*>((char*)SA(b, h) + lds_byte(wr * 64 + m * 16 + fr, k * 32 + fq * 8))
; #define LDB(dst, b, h) for (int n = 0; n < 2; ++n) for (int k = 0; k < 2; ++k) \
;     dst[n][k] = *reinterpret_cast<const bf16x8*>((char*)SB(b, h) + lds_byte(wc * 32 + n * 16 + fr, k * 32 + fq * 8))
; #define MMA(ai, bj, At_, Bt_) do { __builtin_amdgcn_s_setprio(1); \
;     for (int m = 0; m < 4; ++m) for (int n = 0; n < 2; ++n) for (int k = 0; k < 2; ++k) \
;       acc[ai][bj][m][n] = __builtin_amdgcn_mfma_f32_16x16x32_bf16(At_[m][k], Bt_[n][k], acc[ai][bj][m][n], 0, 0, 0); \
;     __builtin_amdgcn_s_setprio(0); } while (0)
; #define WAIT_V(n) asm volatile("s_waitcnt vmcnt(" #n ")" ::: "memory")
; #define WAIT_L(n) asm volatile("s_waitcnt lgkmcnt(" #n ")" ::: "memory")
; #define BAR __builtin_amdgcn_s_barrier()
; #define SCHED __builtin_amdgcn_sched_barrier(0)
; template <int EPI>
; __device__ __forceinline__ void gemm_tile(const GemmArgs& g, int brow, int bcol, int parity, bool first, bool nvalid, int nbrow, int nbcol) {
;     ...
;     LDB(B0, 1, 0); SCHED; LDA(At, 1, 0); STAGE_A(SA(0, 1), brow + HALF, t + 2);
;     WAIT_L(8); BAR; WAIT_L(0); MMA(0, 0, At, B0); BAR; SCHED;
;     LDB(B1, 1, 1); STAGE_B(SB(1, 0), bcol, t + 3);
;     BAR; WAIT_L(0); MMA(0, 1, At, B1); BAR; SCHED;
;     LDA(At, 1, 1); STAGE_A(SA(1, 0), brow, t + 3);
;     BAR; WAIT_L(0); MMA(1, 0, At, B0); BAR; SCHED;
;     STAGE_B(SB(1, 1), bcol + HALF, t + 3);
;     WAIT_V(6); BAR; MMA(1, 1, At, B1); BAR; SCHED;
	s_waitcnt lgkmcnt(0)
	v_mfma_f32_16x16x32_bf16 v[62:65], v[164:167], v[180:183], v[62:65]
	v_mfma_f32_16x16x32_bf16 v[58:61], v[172:175], v[180:183], v[58:61]
	v_mfma_f32_16x16x32_bf16 v[54:57], v[164:167], v[188:191], v[54:57]
	v_mfma_f32_16x16x32_bf16 v[50:53], v[172:175], v[188:191], v[50:53]
	v_mfma_f32_16x16x32_bf16 v[46:49], v[164:167], v[196:199], v[46:49]
	v_mfma_f32_16x16x32_bf16 v[42:45], v[172:175], v[196:199], v[42:45]
	v_mfma_f32_16x16x32_bf16 v[38:41], v[164:167], v[206:209], v[38:41]
	v_mfma_f32_16x16x32_bf16 v[34:37], v[172:175], v[206:209], v[34:37]
	v_mfma_f32_16x16x32_bf16 v[62:65], v[168:171], v[184:187], v[62:65]
	v_mfma_f32_16x16x32_bf16 v[58:61], v[176:179], v[184:187], v[58:61]
	v_mfma_f32_16x16x32_bf16 v[54:57], v[168:171], v[192:195], v[54:57]
	v_mfma_f32_16x16x32_bf16 v[50:53], v[176:179], v[192:195], v[50:53]
	v_mfma_f32_16x16x32_bf16 v[46:49], v[168:171], v[202:205], v[46:49]
	v_mfma_f32_16x16x32_bf16 v[42:45], v[176:179], v[202:205], v[42:45]
	v_mfma_f32_16x16x32_bf16 v[38:41], v[168:171], v[216:219], v[38:41]
	v_mfma_f32_16x16x32_bf16 v[34:37], v[176:179], v[216:219], v[34:37]
	v_mfma_f32_16x16x32_bf16 v[30:33], v[222:225], v[180:183], v[30:33]
	v_mfma_f32_16x16x32_bf16 v[26:29], v[232:235], v[180:183], v[26:29]
	v_mfma_f32_16x16x32_bf16 v[22:25], v[222:225], v[188:191], v[22:25]
	v_mfma_f32_16x16x32_bf16 v[18:21], v[232:235], v[188:191], v[18:21]
	v_mfma_f32_16x16x32_bf16 v[14:17], v[222:225], v[196:199], v[14:17]
	v_mfma_f32_16x16x32_bf16 v[10:13], v[232:235], v[196:199], v[10:13]
	v_mfma_f32_16x16x32_bf16 v[6:9], v[222:225], v[206:209], v[6:9]
	v_mfma_f32_16x16x32_bf16 v[2:5], v[232:235], v[206:209], v[2:5]
	v_mfma_f32_16x16x32_bf16 v[30:33], v[228:231], v[184:187], v[30:33]
	v_mfma_f32_16x16x32_bf16 v[26:29], v[236:239], v[184:187], v[26:29]
	v_mfma_f32_16x16x32_bf16 v[22:25], v[228:231], v[192:195], v[22:25]
	v_mfma_f32_16x16x32_bf16 v[18:21], v[236:239], v[192:195], v[18:21]
	v_mfma_f32_16x16x32_bf16 v[14:17], v[228:231], v[202:205], v[14:17]
	v_mfma_f32_16x16x32_bf16 v[10:13], v[236:239], v[202:205], v[10:13]
	v_mfma_f32_16x16x32_bf16 v[6:9], v[228:231], v[216:219], v[6:9]
	v_mfma_f32_16x16x32_bf16 v[2:5], v[236:239], v[216:219], v[2:5]
	s_barrier
	ds_read_b128 v[164:167], v148
	ds_read_b128 v[168:171], v148 offset:1024
	ds_read_b128 v[172:175], v148 offset:2048
	ds_read_b128 v[176:179], v148 offset:3072
	ds_read_b128 v[180:183], v146 offset:32768
	ds_read_b128 v[184:187], v146 offset:33792
	ds_read_b128 v[188:191], v145 offset:32768
	ds_read_b128 v[192:195], v145 offset:33792
	ds_read_b128 v[196:199], v144 offset:32768
	ds_read_b128 v[202:205], v144 offset:33792
	ds_read_b128 v[206:209], v143 offset:32768
	ds_read_b128 v[216:219], v143 offset:33792
	s_waitcnt lgkmcnt(6)
	ds_read_b128 v[222:225], v147
	ds_read_b128 v[228:231], v147 offset:1024
	ds_read_b128 v[232:235], v147 offset:2048
	ds_read_b128 v[236:239], v147 offset:3072
	v_readfirstlane_b32 s2, v134
	v_lshl_add_u64 v[246:247], v[210:211], 0, s[44:45]
	s_mov_b32 m0, s2
	v_readfirstlane_b32 s2, v133
	global_load_lds_dwordx4 v[246:247], off
	v_lshl_add_u64 v[246:247], v[210:211], 0, s[46:47]
	s_mov_b32 m0, s2
	s_nop 0
	global_load_lds_dwordx4 v[246:247], off
	s_waitcnt vmcnt(8)
	s_barrier
	s_waitcnt lgkmcnt(0)
	v_mfma_f32_16x16x32_bf16 v[126:129], v[164:167], v[180:183], v[126:129]
	v_mfma_f32_16x16x32_bf16 v[122:125], v[172:175], v[180:183], v[122:125]
	v_mfma_f32_16x16x32_bf16 v[118:121], v[164:167], v[188:191], v[118:121]
	v_mfma_f32_16x16x32_bf16 v[114:117], v[172:175], v[188:191], v[114:117]
	v_mfma_f32_16x16x32_bf16 v[110:113], v[164:167], v[196:199], v[110:113]
	v_mfma_f32_16x16x32_bf16 v[106:109], v[172:175], v[196:199], v[106:109]
	v_mfma_f32_16x16x32_bf16 v[102:105], v[164:167], v[206:209], v[102:105]
	v_mfma_f32_16x16x32_bf16 v[98:101], v[172:175], v[206:209], v[98:101]
	v_mfma_f32_16x16x32_bf16 v[126:129], v[168:171], v[184:187], v[126:129]
	v_mfma_f32_16x16x32_bf16 v[122:125], v[176:179], v[184:187], v[122:125]
	v_mfma_f32_16x16x32_bf16 v[118:121], v[168:171], v[192:195], v[118:121]
	v_mfma_f32_16x16x32_bf16 v[114:117], v[176:179], v[192:195], v[114:117]
	v_mfma_f32_16x16x32_bf16 v[110:113], v[168:171], v[202:205], v[110:113]
	v_mfma_f32_16x16x32_bf16 v[106:109], v[176:179], v[202:205], v[106:109]
	v_mfma_f32_16x16x32_bf16 v[102:105], v[168:171], v[216:219], v[102:105]
	v_mfma_f32_16x16x32_bf16 v[98:101], v[176:179], v[216:219], v[98:101]
	v_mfma_f32_16x16x32_bf16 v[94:97], v[222:225], v[180:183], v[94:97]
	v_mfma_f32_16x16x32_bf16 v[90:93], v[232:235], v[180:183], v[90:93]
	v_mfma_f32_16x16x32_bf16 v[86:89], v[222:225], v[188:191], v[86:89]
	v_mfma_f32_16x16x32_bf16 v[82:85], v[232:235], v[188:191], v[82:85]
	v_mfma_f32_16x16x32_bf16 v[78:81], v[222:225], v[196:199], v[78:81]
	v_mfma_f32_16x16x32_bf16 v[74:77], v[232:235], v[196:199], v[74:77]
	v_mfma_f32_16x16x32_bf16 v[70:73], v[222:225], v[206:209], v[70:73]
	v_mfma_f32_16x16x32_bf16 v[66:69], v[232:235], v[206:209], v[66:69]
	v_mfma_f32_16x16x32_bf16 v[94:97], v[228:231], v[184:187], v[94:97]
	v_mfma_f32_16x16x32_bf16 v[90:93], v[236:239], v[184:187], v[90:93]
	v_mfma_f32_16x16x32_bf16 v[86:89], v[228:231], v[192:195], v[86:89]
	v_mfma_f32_16x16x32_bf16 v[82:85], v[236:239], v[192:195], v[82:85]
	v_mfma_f32_16x16x32_bf16 v[78:81], v[228:231], v[202:205], v[78:81]
	v_mfma_f32_16x16x32_bf16 v[74:77], v[236:239], v[202:205], v[74:77]
	v_mfma_f32_16x16x32_bf16 v[70:73], v[228:231], v[216:219], v[70:73]
	v_mfma_f32_16x16x32_bf16 v[66:69], v[236:239], v[216:219], v[66:69]
	s_barrier
; #define STAGE_B(P, br, kt) do { const char* _gb = (const char*)(Bt + ((long)(br) * K + (long)(kt) * BK)); \
;     __builtin_amdgcn_global_load_lds((const unsigned*)(_gb + bofl0), (unsigned*)((char*)(P) + gtid_ * 16), 16, 0, 0); \
;     __builtin_amdgcn_global_load_lds((const unsigned*)(_gb + (long)K * 128 + bofl0), (unsigned*)((char*)(P) + gtid_ * 16 + 8192), 16, 0, 0); } while (0)
; #define LDA(dst, b, h) for (int m = 0; m < 4; ++m) for (int k = 0; k < 2; ++k) \
;     dst[m][k] = *reinterpret_cast<const bf16x8*>((char*)SA(b, h) + lds_byte(wr * 64 + m * 16 + fr, k * 32 + fq * 8))
; #define LDB(dst, b, h) for (int n = 0; n < 2; ++n) for (int k = 0; k < 2; ++k) \
;     dst[n][k] = *reinterpret_cast<const bf16x8*>((char*)SB(b, h) + lds_byte(wc * 32 + n * 16 + fr, k * 32 + fq * 8))
; #define MMA(ai, bj, At_, Bt_) do { __builtin_amdgcn_s_setprio(1); \
;     for (int m = 0; m < 4; ++m) for (int n = 0; n < 2; ++n) for (int k = 0; k < 2; ++k) \
;       acc[ai][bj][m][n] = __builtin_amdgcn_mfma_f32_16x16x32_bf16(At_[m][k], Bt_[n][k], acc[ai][bj][m][n], 0, 0, 0); \
;     __builtin_amdgcn_s_setprio(0); } while (0)
; #define WAIT_V(n) asm volatile("s_waitcnt vmcnt(" #n ")" ::: "memory")
; #define WAIT_L(n) asm volatile("s_waitcnt lgkmcnt(" #n ")" ::: "memory")
; #define BAR __builtin_amdgcn_s_barrier()
; #define SCHED __builtin_amdgcn_sched_barrier(0)
; template <int EPI>
; __device__ __forceinline__ void gemm_tile(const GemmArgs& g, int brow, int bcol, int parity, bool first, bool nvalid, int nbrow, int nbcol) {
;     ...
;     BAR; WAIT_L(0); MMA(0, 1, At, B1); BAR; SCHED;
;     LDA(At, 1, 1); STAGE_A(SA(1, 0), brow, t + 3);
;     BAR; WAIT_L(0); MMA(1, 0, At, B0); BAR; SCHED;
;     STAGE_B(SB(1, 1), bcol + HALF, t + 3);
;     WAIT_V(6); BAR; MMA(1, 1, At, B1); BAR; SCHED;
;   }
;   { LDB(B0, 0, 0); LDA(At, 0, 0); STAGE_A(SA(1, 1), brow + HALF, nt - 1);
;     BAR; WAIT_L(0); MMA(0, 0, At, B0); BAR;
;     LDB(B1, 0, 1); BAR; WAIT_L(0); MMA(0, 1, At, B1); BAR; SCHED;
;     LDA(At, 0, 1); WAIT_V(4); BAR; WAIT_L(0); MMA(1, 0, At, B0); MMA(1, 1, At, B1); BAR; }
	ds_read_b128 v[180:183], v146 offset:49152
	ds_read_b128 v[184:187], v146 offset:50176
	ds_read_b128 v[188:191], v145 offset:49152
	ds_read_b128 v[192:195], v145 offset:50176
	ds_read_b128 v[196:199], v144 offset:49152
	ds_read_b128 v[202:205], v144 offset:50176
	ds_read_b128 v[206:209], v143 offset:49152
	ds_read_b128 v[216:219], v143 offset:50176
	v_readfirstlane_b32 s2, v149
	v_lshl_add_u64 v[240:241], v[212:213], 0, s[58:59]
	s_mov_b32 m0, s2
	v_readfirstlane_b32 s2, v151
	global_load_lds_dwordx4 v[240:241], off
	v_lshl_add_u64 v[240:241], v[212:213], 0, s[76:77]
	s_mov_b32 m0, s2
	s_nop 0
	global_load_lds_dwordx4 v[240:241], off
	v_readfirstlane_b32 s2, v152
	v_lshl_add_u64 v[240:241], v[210:211], 0, s[48:49]
	s_mov_b32 m0, s2
	v_readfirstlane_b32 s2, v153
	global_load_lds_dwordx4 v[240:241], off
	v_lshl_add_u64 v[210:211], v[210:211], 0, s[50:51]
	s_mov_b32 m0, s2
	s_nop 0
	global_load_lds_dwordx4 v[210:211], off
	v_readfirstlane_b32 s2, v155
	v_lshl_add_u64 v[244:245], v[212:213], 0, s[96:97]
	s_mov_b32 m0, s2
	v_readfirstlane_b32 s2, v156
	global_load_lds_dwordx4 v[244:245], off
	v_lshl_add_u64 v[244:245], v[212:213], 0, s[60:61]
	s_mov_b32 m0, s2
	s_nop 0
	global_load_lds_dwordx4 v[244:245], off
	s_waitcnt vmcnt(8)
	s_barrier
	s_waitcnt lgkmcnt(0)
	v_mfma_f32_16x16x32_bf16 v[62:65], v[164:167], v[180:183], v[62:65]
	v_mfma_f32_16x16x32_bf16 v[58:61], v[172:175], v[180:183], v[58:61]
	v_mfma_f32_16x16x32_bf16 v[54:57], v[164:167], v[188:191], v[54:57]
	v_mfma_f32_16x16x32_bf16 v[50:53], v[172:175], v[188:191], v[50:53]
	v_mfma_f32_16x16x32_bf16 v[46:49], v[164:167], v[196:199], v[46:49]
	v_mfma_f32_16x16x32_bf16 v[42:45], v[172:175], v[196:199], v[42:45]
	v_mfma_f32_16x16x32_bf16 v[38:41], v[164:167], v[206:209], v[38:41]
	v_mfma_f32_16x16x32_bf16 v[34:37], v[172:175], v[206:209], v[34:37]
	v_mfma_f32_16x16x32_bf16 v[62:65], v[168:171], v[184:187], v[62:65]
	v_mfma_f32_16x16x32_bf16 v[58:61], v[176:179], v[184:187], v[58:61]
	v_mfma_f32_16x16x32_bf16 v[54:57], v[168:171], v[192:195], v[54:57]
	v_mfma_f32_16x16x32_bf16 v[50:53], v[176:179], v[192:195], v[50:53]
	v_mfma_f32_16x16x32_bf16 v[46:49], v[168:171], v[202:205], v[46:49]
	v_mfma_f32_16x16x32_bf16 v[42:45], v[176:179], v[202:205], v[42:45]
	v_mfma_f32_16x16x32_bf16 v[38:41], v[168:171], v[216:219], v[38:41]
	v_mfma_f32_16x16x32_bf16 v[34:37], v[176:179], v[216:219], v[34:37]
	v_mfma_f32_16x16x32_bf16 v[30:33], v[222:225], v[180:183], v[30:33]
	v_mfma_f32_16x16x32_bf16 v[26:29], v[232:235], v[180:183], v[26:29]
	v_mfma_f32_16x16x32_bf16 v[22:25], v[222:225], v[188:191], v[22:25]
	v_mfma_f32_16x16x32_bf16 v[18:21], v[232:235], v[188:191], v[18:21]
	v_mfma_f32_16x16x32_bf16 v[14:17], v[222:225], v[196:199], v[14:17]
	v_mfma_f32_16x16x32_bf16 v[10:13], v[232:235], v[196:199], v[10:13]
	v_mfma_f32_16x16x32_bf16 v[6:9], v[222:225], v[206:209], v[6:9]
	v_mfma_f32_16x16x32_bf16 v[2:5], v[232:235], v[206:209], v[2:5]
	v_mfma_f32_16x16x32_bf16 v[30:33], v[228:231], v[184:187], v[30:33]
	v_mfma_f32_16x16x32_bf16 v[26:29], v[236:239], v[184:187], v[26:29]
	v_mfma_f32_16x16x32_bf16 v[22:25], v[228:231], v[192:195], v[22:25]
	v_mfma_f32_16x16x32_bf16 v[18:21], v[236:239], v[192:195], v[18:21]
	v_mfma_f32_16x16x32_bf16 v[14:17], v[228:231], v[202:205], v[14:17]
	v_mfma_f32_16x16x32_bf16 v[10:13], v[236:239], v[202:205], v[10:13]
	v_mfma_f32_16x16x32_bf16 v[6:9], v[228:231], v[216:219], v[6:9]
	v_mfma_f32_16x16x32_bf16 v[2:5], v[236:239], v[216:219], v[2:5]
	s_barrier
	s_add_i32 s22, s22, 2
	s_add_u32 s12, s12, 0x100
	s_addc_u32 s13, s13, 0
	s_add_u32 s0, s0, 0x100
	s_addc_u32 s1, s1, 0
	s_cmp_lt_u32 s22, 12
	s_cbranch_scc1 .LBB0_133
	s_or_b32 s0, s40, 0x80
	s_ashr_i32 s1, s0, 31
	s_lshl_b64 s[0:1], s[0:1], 11
	s_add_u32 s0, s80, s0
	s_addc_u32 s1, s81, s1
	v_lshl_add_u64 v[130:131], s[0:1], 0, v[0:1]
	s_mov_b64 s[0:1], 0x780
	v_lshl_add_u64 v[152:153], v[130:131], 0, s[0:1]
	v_readfirstlane_b32 s0, v161
	s_mov_b32 m0, s0
	s_mov_b64 s[0:1], 0x20780
	v_lshl_add_u64 v[130:131], v[130:131], 0, s[0:1]
	v_readfirstlane_b32 s0, v162
	ds_read_b128 v[164:167], v157
	ds_read_b128 v[168:171], v157 offset:1024
	ds_read_b128 v[172:175], v157 offset:2048
	ds_read_b128 v[176:179], v157 offset:3072
	ds_read_b128 v[180:183], v146
	ds_read_b128 v[184:187], v146 offset:1024
	ds_read_b128 v[188:191], v145
	ds_read_b128 v[192:195], v145 offset:1024
	ds_read_b128 v[196:199], v144
	ds_read_b128 v[202:205], v144 offset:1024
	ds_read_b128 v[206:209], v143
	ds_read_b128 v[216:219], v143 offset:1024
	global_load_lds_dwordx4 v[152:153], off
	s_mov_b32 m0, s0
	s_nop 0
	global_load_lds_dwordx4 v[130:131], off
	s_waitcnt vmcnt(8)
	s_barrier
	s_waitcnt lgkmcnt(0)
	s_setprio 1
	s_waitcnt lgkmcnt(0)
	v_mfma_f32_16x16x32_bf16 v[126:129], v[164:167], v[180:183], v[126:129]
	v_mfma_f32_16x16x32_bf16 v[122:125], v[172:175], v[180:183], v[122:125]
	v_mfma_f32_16x16x32_bf16 v[110:113], v[164:167], v[196:199], v[110:113]
	v_mfma_f32_16x16x32_bf16 v[106:109], v[172:175], v[196:199], v[106:109]
	v_mfma_f32_16x16x32_bf16 v[126:129], v[168:171], v[184:187], v[126:129]
	v_mfma_f32_16x16x32_bf16 v[122:125], v[176:179], v[184:187], v[122:125]
	v_mfma_f32_16x16x32_bf16 v[118:121], v[164:167], v[188:191], v[118:121]
	v_mfma_f32_16x16x32_bf16 v[114:117], v[172:175], v[188:191], v[114:117]
	v_mfma_f32_16x16x32_bf16 v[110:113], v[168:171], v[202:205], v[110:113]
	v_mfma_f32_16x16x32_bf16 v[106:109], v[176:179], v[202:205], v[106:109]
	v_mfma_f32_16x16x32_bf16 v[102:105], v[164:167], v[206:209], v[102:105]
	v_mfma_f32_16x16x32_bf16 v[98:101], v[172:175], v[206:209], v[98:101]
	v_mfma_f32_16x16x32_bf16 v[222:225], v[168:171], v[192:195], v[118:121]
	v_mfma_f32_16x16x32_bf16 v[228:231], v[176:179], v[192:195], v[114:117]
	v_mfma_f32_16x16x32_bf16 v[232:235], v[168:171], v[216:219], v[102:105]
	v_mfma_f32_16x16x32_bf16 v[236:239], v[176:179], v[216:219], v[98:101]
	s_setprio 0
	s_barrier
; #define LDA(dst, b, h) for (int m = 0; m < 4; ++m) for (int k = 0; k < 2; ++k) \
;     dst[m][k] = *reinterpret_cast<const bf16x8*>((char*)SA(b, h) + lds_byte(wr * 64 + m * 16 + fr, k * 32 + fq * 8))
; #define LDB(dst, b, h) for (int n = 0; n < 2; ++n) for (int k = 0; k < 2; ++k) \
;     dst[n][k] = *reinterpret_cast<const bf16x8*>((char*)SB(b, h) + lds_byte(wc * 32 + n * 16 + fr, k * 32 + fq * 8))
; #define MMA(ai, bj, At_, Bt_) do { __builtin_amdgcn_s_setprio(1); \
;     for (int m = 0; m < 4; ++m) for (int n = 0; n < 2; ++n) for (int k = 0; k < 2; ++k) \
;       acc[ai][bj][m][n] = __builtin_amdgcn_mfma_f32_16x16x32_bf16(At_[m][k], Bt_[n][k], acc[ai][bj][m][n], 0, 0, 0); \
;     __builtin_amdgcn_s_setprio(0); } while (0)
; #define WAIT_V(n) asm volatile("s_waitcnt vmcnt(" #n ")" ::: "memory")
; #define WAIT_L(n) asm volatile("s_waitcnt lgkmcnt(" #n ")" ::: "memory")
; #define BAR __builtin_amdgcn_s_barrier()
; #define SCHED __builtin_amdgcn_sched_barrier(0)
; template <int EPI>
; __device__ __forceinline__ void gemm_tile(const GemmArgs& g, int brow, int bcol, int parity, bool first, bool nvalid, int nbrow, int nbcol) {
;     ...
;   { LDB(B0, 0, 0); LDA(At, 0, 0); STAGE_A(SA(1, 1), brow + HALF, nt - 1);
;     BAR; WAIT_L(0); MMA(0, 0, At, B0); BAR;
;     LDB(B1, 0, 1); BAR; WAIT_L(0); MMA(0, 1, At, B1); BAR; SCHED;
;     LDA(At, 0, 1); WAIT_V(4); BAR; WAIT_L(0); MMA(1, 0, At, B0); MMA(1, 1, At, B1); BAR; }
;   { LDB(B0, 1, 0); LDA(At, 1, 0); WAIT_V(2); BAR; WAIT_L(0); MMA(0, 0, At, B0); BAR;
;     LDB(B1, 1, 1); WAIT_V(0); BAR; WAIT_L(0); MMA(0, 1, At, B1); BAR; SCHED;
	s_nop 1
	ds_read_b128 v[98:101], v154
	ds_read_b128 v[102:105], v154 offset:1024
	ds_read_b128 v[114:117], v154 offset:2048
	ds_read_b128 v[118:121], v154 offset:3072
	s_barrier
	s_waitcnt lgkmcnt(0)
	s_setprio 1
	s_waitcnt lgkmcnt(0)
	v_mfma_f32_16x16x32_bf16 v[94:97], v[98:101], v[180:183], v[94:97]
	v_mfma_f32_16x16x32_bf16 v[90:93], v[114:117], v[180:183], v[90:93]
	v_mfma_f32_16x16x32_bf16 v[78:81], v[98:101], v[196:199], v[78:81]
	v_mfma_f32_16x16x32_bf16 v[74:77], v[114:117], v[196:199], v[74:77]
	v_mfma_f32_16x16x32_bf16 v[94:97], v[102:105], v[184:187], v[94:97]
	v_mfma_f32_16x16x32_bf16 v[90:93], v[118:121], v[184:187], v[90:93]
	v_mfma_f32_16x16x32_bf16 v[86:89], v[98:101], v[188:191], v[86:89]
	v_mfma_f32_16x16x32_bf16 v[82:85], v[114:117], v[188:191], v[82:85]
	v_mfma_f32_16x16x32_bf16 v[78:81], v[102:105], v[202:205], v[78:81]
	v_mfma_f32_16x16x32_bf16 v[74:77], v[118:121], v[202:205], v[74:77]
	v_mfma_f32_16x16x32_bf16 v[70:73], v[98:101], v[206:209], v[70:73]
	v_mfma_f32_16x16x32_bf16 v[66:69], v[114:117], v[206:209], v[66:69]
	v_mfma_f32_16x16x32_bf16 v[152:155], v[102:105], v[192:195], v[86:89]
	v_mfma_f32_16x16x32_bf16 v[180:183], v[118:121], v[192:195], v[82:85]
	v_mfma_f32_16x16x32_bf16 v[184:187], v[102:105], v[216:219], v[70:73]
	v_mfma_f32_16x16x32_bf16 v[188:191], v[118:121], v[216:219], v[66:69]
	s_setprio 0
	s_barrier
	s_nop 1
	ds_read_b128 v[66:69], v146 offset:16384
	ds_read_b128 v[70:73], v146 offset:17408
	ds_read_b128 v[82:85], v145 offset:16384
	ds_read_b128 v[86:89], v145 offset:17408
	ds_read_b128 v[192:195], v144 offset:16384
	ds_read_b128 v[196:199], v144 offset:17408
	ds_read_b128 v[202:205], v143 offset:16384
	ds_read_b128 v[206:209], v143 offset:17408
	s_waitcnt vmcnt(4)
	s_barrier
	s_waitcnt lgkmcnt(0)
	s_setprio 1
	s_waitcnt lgkmcnt(0)
	v_mfma_f32_16x16x32_bf16 v[62:65], v[164:167], v[66:69], v[62:65]
	v_mfma_f32_16x16x32_bf16 v[58:61], v[172:175], v[66:69], v[58:61]
	v_mfma_f32_16x16x32_bf16 v[46:49], v[164:167], v[192:195], v[46:49]
	v_mfma_f32_16x16x32_bf16 v[42:45], v[172:175], v[192:195], v[42:45]
	v_mfma_f32_16x16x32_bf16 v[62:65], v[168:171], v[70:73], v[62:65]
	v_mfma_f32_16x16x32_bf16 v[58:61], v[176:179], v[70:73], v[58:61]
	v_mfma_f32_16x16x32_bf16 v[54:57], v[164:167], v[82:85], v[54:57]
	v_mfma_f32_16x16x32_bf16 v[50:53], v[172:175], v[82:85], v[50:53]
	v_mfma_f32_16x16x32_bf16 v[46:49], v[168:171], v[196:199], v[46:49]
	v_mfma_f32_16x16x32_bf16 v[42:45], v[176:179], v[196:199], v[42:45]
	v_mfma_f32_16x16x32_bf16 v[38:41], v[164:167], v[202:205], v[38:41]
	v_mfma_f32_16x16x32_bf16 v[34:37], v[172:175], v[202:205], v[34:37]
	v_mfma_f32_16x16x32_bf16 v[216:219], v[168:171], v[86:89], v[54:57]
	v_mfma_f32_16x16x32_bf16 v[240:243], v[176:179], v[86:89], v[50:53]
	v_mfma_f32_16x16x32_bf16 v[162:165], v[168:171], v[206:209], v[38:41]
	v_mfma_f32_16x16x32_bf16 v[166:169], v[176:179], v[206:209], v[34:37]
	s_setprio 0
	s_setprio 1
	v_mfma_f32_16x16x32_bf16 v[30:33], v[98:101], v[66:69], v[30:33]
	v_mfma_f32_16x16x32_bf16 v[26:29], v[114:117], v[66:69], v[26:29]
	v_mfma_f32_16x16x32_bf16 v[14:17], v[98:101], v[192:195], v[14:17]
	v_mfma_f32_16x16x32_bf16 v[10:13], v[114:117], v[192:195], v[10:13]
	v_mfma_f32_16x16x32_bf16 v[30:33], v[102:105], v[70:73], v[30:33]
	v_mfma_f32_16x16x32_bf16 v[26:29], v[118:121], v[70:73], v[26:29]
	v_mfma_f32_16x16x32_bf16 v[22:25], v[98:101], v[82:85], v[22:25]
	v_mfma_f32_16x16x32_bf16 v[18:21], v[114:117], v[82:85], v[18:21]
	v_mfma_f32_16x16x32_bf16 v[14:17], v[102:105], v[196:199], v[14:17]
	v_mfma_f32_16x16x32_bf16 v[10:13], v[118:121], v[196:199], v[10:13]
	v_mfma_f32_16x16x32_bf16 v[6:9], v[98:101], v[202:205], v[6:9]
	v_mfma_f32_16x16x32_bf16 v[2:5], v[114:117], v[202:205], v[2:5]
	v_mfma_f32_16x16x32_bf16 v[170:173], v[102:105], v[86:89], v[22:25]
	v_mfma_f32_16x16x32_bf16 v[174:177], v[118:121], v[86:89], v[18:21]
	v_mfma_f32_16x16x32_bf16 v[192:195], v[102:105], v[206:209], v[6:9]
	v_mfma_f32_16x16x32_bf16 v[196:199], v[118:121], v[206:209], v[2:5]
	s_setprio 0
	s_barrier
	s_nop 1
	ds_read_b128 v[2:5], v148
	ds_read_b128 v[6:9], v148 offset:1024
	ds_read_b128 v[202:205], v148 offset:2048
	ds_read_b128 v[206:209], v148 offset:3072
	ds_read_b128 v[18:21], v146 offset:32768
	ds_read_b128 v[22:25], v146 offset:33792
	ds_read_b128 v[34:37], v145 offset:32768
	ds_read_b128 v[38:41], v145 offset:33792
	ds_read_b128 v[50:53], v144 offset:32768
	ds_read_b128 v[54:57], v144 offset:33792
	ds_read_b128 v[244:247], v143 offset:32768
	ds_read_b128 v[248:251], v143 offset:33792
	s_waitcnt vmcnt(2)
	s_barrier
; #define LDA(dst, b, h) for (int m = 0; m < 4; ++m) for (int k = 0; k < 2; ++k) \
;     dst[m][k] = *reinterpret_cast<const bf16x8*>((char*)SA(b, h) + lds_byte(wr * 64 + m * 16 + fr, k * 32 + fq * 8))
; #define LDB(dst, b, h) for (int n = 0; n < 2; ++n) for (int k = 0; k < 2; ++k) \
;     dst[n][k] = *reinterpret_cast<const bf16x8*>((char*)SB(b, h) + lds_byte(wc * 32 + n * 16 + fr, k * 32 + fq * 8))
; #define MMA(ai, bj, At_, Bt_) do { __builtin_amdgcn_s_setprio(1); \
;     for (int m = 0; m < 4; ++m) for (int n = 0; n < 2; ++n) for (int k = 0; k < 2; ++k) \
;       acc[ai][bj][m][n] = __builtin_amdgcn_mfma_f32_16x16x32_bf16(At_[m][k], Bt_[n][k], acc[ai][bj][m][n], 0, 0, 0); \
;     __builtin_amdgcn_s_setprio(0); } while (0)
; #define WAIT_V(n) asm volatile("s_waitcnt vmcnt(" #n ")" ::: "memory")
; #define WAIT_L(n) asm volatile("s_waitcnt lgkmcnt(" #n ")" ::: "memory")
; #define BAR __builtin_amdgcn_s_barrier()
; #define SCHED __builtin_amdgcn_sched_barrier(0)
; template <int EPI>
; __device__ __forceinline__ void gemm_tile(const GemmArgs& g, int brow, int bcol, int parity, bool first, bool nvalid, int nbrow, int nbcol) {
;     ...
;     LDA(At, 0, 1); WAIT_V(4); BAR; WAIT_L(0); MMA(1, 0, At, B0); MMA(1, 1, At, B1); BAR; }
;   { LDB(B0, 1, 0); LDA(At, 1, 0); WAIT_V(2); BAR; WAIT_L(0); MMA(0, 0, At, B0); BAR;
;     LDB(B1, 1, 1); WAIT_V(0); BAR; WAIT_L(0); MMA(0, 1, At, B1); BAR; SCHED;
;     LDA(At, 1, 1); BAR; WAIT_L(0); MMA(1, 0, At, B0); MMA(1, 1, At, B1); BAR; }
;   if (wr == 0) BAR;
	s_waitcnt lgkmcnt(0)
	s_setprio 1
	s_waitcnt lgkmcnt(0)
	v_mfma_f32_16x16x32_bf16 v[66:69], v[2:5], v[18:21], v[126:129]
	v_mfma_f32_16x16x32_bf16 v[114:117], v[6:9], v[22:25], v[66:69]
	v_mfma_f32_16x16x32_bf16 v[66:69], v[202:205], v[18:21], v[122:125]
	v_mfma_f32_16x16x32_bf16 v[118:121], v[206:209], v[22:25], v[66:69]
	v_mfma_f32_16x16x32_bf16 v[66:69], v[2:5], v[34:37], v[222:225]
	v_mfma_f32_16x16x32_bf16 v[98:101], v[6:9], v[38:41], v[66:69]
	v_mfma_f32_16x16x32_bf16 v[66:69], v[202:205], v[34:37], v[228:231]
	v_mfma_f32_16x16x32_bf16 v[102:105], v[206:209], v[38:41], v[66:69]
	v_mfma_f32_16x16x32_bf16 v[66:69], v[2:5], v[50:53], v[110:113]
	v_mfma_f32_16x16x32_bf16 v[82:85], v[6:9], v[54:57], v[66:69]
	v_mfma_f32_16x16x32_bf16 v[66:69], v[202:205], v[50:53], v[106:109]
	v_mfma_f32_16x16x32_bf16 v[86:89], v[206:209], v[54:57], v[66:69]
	v_mfma_f32_16x16x32_bf16 v[66:69], v[2:5], v[244:247], v[232:235]
	v_mfma_f32_16x16x32_bf16 v[70:73], v[202:205], v[244:247], v[236:239]
	v_mfma_f32_16x16x32_bf16 v[66:69], v[6:9], v[248:251], v[66:69]
	v_mfma_f32_16x16x32_bf16 v[70:73], v[206:209], v[248:251], v[70:73]
	s_setprio 0
	s_barrier
	ds_read_b128 v[222:225], v147
	ds_read_b128 v[228:231], v147 offset:1024
	ds_read_b128 v[232:235], v147 offset:2048
	ds_read_b128 v[236:239], v147 offset:3072
	s_waitcnt vmcnt(0)
	s_barrier
	s_waitcnt lgkmcnt(0)
	s_setprio 1
	s_waitcnt lgkmcnt(0)
	v_mfma_f32_16x16x32_bf16 v[94:97], v[222:225], v[18:21], v[94:97]
	v_mfma_f32_16x16x32_bf16 v[18:21], v[232:235], v[18:21], v[90:93]
	v_mfma_f32_16x16x32_bf16 v[122:125], v[236:239], v[22:25], v[18:21]
	v_mfma_f32_16x16x32_bf16 v[18:21], v[222:225], v[34:37], v[152:155]
	v_mfma_f32_16x16x32_bf16 v[110:113], v[228:231], v[38:41], v[18:21]
	v_mfma_f32_16x16x32_bf16 v[18:21], v[232:235], v[34:37], v[180:183]
	v_mfma_f32_16x16x32_bf16 v[106:109], v[236:239], v[38:41], v[18:21]
	v_mfma_f32_16x16x32_bf16 v[18:21], v[222:225], v[50:53], v[78:81]
	v_mfma_f32_16x16x32_bf16 v[126:129], v[228:231], v[22:25], v[94:97]
	v_mfma_f32_16x16x32_bf16 v[94:97], v[228:231], v[54:57], v[18:21]
	v_mfma_f32_16x16x32_bf16 v[18:21], v[232:235], v[50:53], v[74:77]
	v_mfma_f32_16x16x32_bf16 v[90:93], v[236:239], v[54:57], v[18:21]
	v_mfma_f32_16x16x32_bf16 v[18:21], v[222:225], v[244:247], v[184:187]
	v_mfma_f32_16x16x32_bf16 v[78:81], v[228:231], v[248:251], v[18:21]
	v_mfma_f32_16x16x32_bf16 v[18:21], v[232:235], v[244:247], v[188:191]
	v_mfma_f32_16x16x32_bf16 v[74:77], v[236:239], v[248:251], v[18:21]
	s_setprio 0
	s_barrier
	ds_read_b128 v[152:155], v146 offset:49152
	ds_read_b128 v[146:149], v146 offset:50176
	ds_read_b128 v[178:181], v145 offset:49152
	ds_read_b128 v[182:185], v145 offset:50176
	ds_read_b128 v[186:189], v144 offset:49152
	ds_read_b128 v[244:247], v144 offset:50176
	ds_read_b128 v[248:251], v143 offset:49152
	ds_read_b128 v[210:213], v143 offset:50176
	s_barrier
	s_waitcnt lgkmcnt(0)
	s_setprio 1
	s_waitcnt lgkmcnt(0)
	v_mfma_f32_16x16x32_bf16 v[18:21], v[2:5], v[152:155], v[62:65]
	v_mfma_f32_16x16x32_bf16 v[50:53], v[6:9], v[146:149], v[18:21]
	v_mfma_f32_16x16x32_bf16 v[18:21], v[202:205], v[152:155], v[58:61]
	v_mfma_f32_16x16x32_bf16 v[54:57], v[206:209], v[146:149], v[18:21]
	v_mfma_f32_16x16x32_bf16 v[18:21], v[2:5], v[178:181], v[216:219]
	v_mfma_f32_16x16x32_bf16 v[34:37], v[6:9], v[182:185], v[18:21]
	v_mfma_f32_16x16x32_bf16 v[18:21], v[202:205], v[178:181], v[240:243]
	v_mfma_f32_16x16x32_bf16 v[38:41], v[206:209], v[182:185], v[18:21]
	v_mfma_f32_16x16x32_bf16 v[18:21], v[2:5], v[186:189], v[46:49]
	v_mfma_f32_16x16x32_bf16 v[2:5], v[2:5], v[248:251], v[162:165]
	v_mfma_f32_16x16x32_bf16 v[18:21], v[6:9], v[244:247], v[18:21]
	v_mfma_f32_16x16x32_bf16 v[22:25], v[202:205], v[186:189], v[42:45]
	v_mfma_f32_16x16x32_bf16 v[2:5], v[6:9], v[210:213], v[2:5]
	v_mfma_f32_16x16x32_bf16 v[6:9], v[202:205], v[248:251], v[166:169]
	v_mfma_f32_16x16x32_bf16 v[22:25], v[206:209], v[244:247], v[22:25]
	v_mfma_f32_16x16x32_bf16 v[6:9], v[206:209], v[210:213], v[6:9]
	s_setprio 0
	s_setprio 1
	v_mfma_f32_16x16x32_bf16 v[26:29], v[232:235], v[152:155], v[26:29]
	v_mfma_f32_16x16x32_bf16 v[58:61], v[236:239], v[146:149], v[26:29]
	v_mfma_f32_16x16x32_bf16 v[26:29], v[222:225], v[178:181], v[170:173]
	v_mfma_f32_16x16x32_bf16 v[46:49], v[228:231], v[182:185], v[26:29]
	v_mfma_f32_16x16x32_bf16 v[26:29], v[232:235], v[178:181], v[174:177]
	v_mfma_f32_16x16x32_bf16 v[10:13], v[232:235], v[186:189], v[10:13]
	v_mfma_f32_16x16x32_bf16 v[30:33], v[222:225], v[152:155], v[30:33]
	v_mfma_f32_16x16x32_bf16 v[42:45], v[236:239], v[182:185], v[26:29]
	v_mfma_f32_16x16x32_bf16 v[14:17], v[222:225], v[186:189], v[14:17]
	v_mfma_f32_16x16x32_bf16 v[26:29], v[236:239], v[244:247], v[10:13]
	v_mfma_f32_16x16x32_bf16 v[10:13], v[222:225], v[248:251], v[192:195]
	v_mfma_f32_16x16x32_bf16 v[62:65], v[228:231], v[146:149], v[30:33]
	v_mfma_f32_16x16x32_bf16 v[30:33], v[228:231], v[244:247], v[14:17]
	v_mfma_f32_16x16x32_bf16 v[14:17], v[228:231], v[210:213], v[10:13]
	v_mfma_f32_16x16x32_bf16 v[10:13], v[232:235], v[248:251], v[196:199]
	v_mfma_f32_16x16x32_bf16 v[10:13], v[236:239], v[210:213], v[10:13]
	s_setprio 0
	s_movk_i32 s0, 0x100
	v_cmp_gt_u32_e32 vcc, s0, v138
	s_barrier
	s_and_saveexec_b64 s[0:1], vcc
	s_cbranch_execz .LBB0_136
	s_barrier

; #define SCHED __builtin_amdgcn_sched_barrier(0)
; template <int EPI>
; __device__ __forceinline__ void gemm_tile(const GemmArgs& g, int brow, int bcol, int parity, bool first, bool nvalid, int nbrow, int nbcol) {
;     ...
;     } else {
;       _Pragma("unroll") for (int ai = 0; ai < 2; ++ai) _Pragma("unroll") for (int bj = 0; bj < 2; ++bj) {
;         SCHED;
;         _Pragma("unroll") for (int m = 0; m < 4; ++m) _Pragma("unroll") for (int j = 0; j < 4; ++j) {
;           const float rs = rstd_s[lrow0 + ai * HALF + m * 16 + fq * 4 + j];
;           _Pragma("unroll") for (int n = 0; n < 2; ++n) W_WRITE(m, n, j, acc[ai][bj][m][n][j] * rs);
;         }
;         bfu* dst = g.outb + (long)(wrow0 + ai * HALF) * g.ldo + wcol0 + bj * HALF;
;         W_STORE_BF16(dst, g.ldo);
;       }
.LBB0_138:
	v_mbcnt_lo_u32_b32 v130, -1, 0
	v_mbcnt_hi_u32_b32 v130, -1, v130
	s_add_i32 s19, s19, 1
	s_and_b32 s2, s33, 0x100
	s_add_i32 s2, s2, s14
	v_and_b32_e32 v131, 15, v130
	v_lshrrev_b32_e32 v132, 4, v130
	v_lshl_add_u32 v133, v131, 2, s2
	ds_read_b32 v138, v133
	ds_read_b32 v139, v133 offset:64
	ds_read_b32 v140, v133 offset:128
	ds_read_b32 v141, v133 offset:192
	ds_read_b32 v142, v133 offset:512
	ds_read_b32 v143, v133 offset:576
	ds_read_b32 v144, v133 offset:640
	ds_read_b32 v145, v133 offset:704
	v_lshlrev_b32_e32 v134, 4, v132
	v_lshlrev_b32_e32 v135, 2, v132
	v_and_b32_e32 v134, 16, v134
	v_and_b32_e32 v135, 8, v135
	s_and_b32 s3, s21, 0x7fffff8
	s_lshl_b32 s3, s3, 5
	s_lshr_b32 s12, s33, 1
	s_and_b32 s12, s12, 0x60
	s_add_i32 s3, s3, s12
	v_or_b32_e32 v134, v134, v135
	v_add_lshl_u32 v134, v134, s3, 1
	v_mov_b32_e32 v135, 0
	s_lshr_b32 s12, s33, 2
	s_and_b32 s12, s12, 64
	s_add_i32 s12, s12, s40
	v_add_u32_e32 v136, s12, v131
	s_movk_i32 s3, 0x2400
	v_mad_u64_u32 v[134:135], vcc, v136, s3, v[134:135]
	v_lshl_add_u64 v[134:135], v[134:135], 0, s[16:17]
	s_mov_b64 s[12:13], 0x24000
	s_mov_b64 s[14:15], 0xb4000
	s_waitcnt lgkmcnt(0)
	s_cmpk_lt_i32 s38, 0xc00
	s_cbranch_scc1 .Lswa_epi_rope
	v_pk_mul_f32 v[114:115], v[114:115], v[138:139] op_sel_hi:[1,0]
	v_pk_mul_f32 v[116:117], v[116:117], v[138:139] op_sel_hi:[1,0]
	v_pk_mul_f32 v[118:119], v[118:119], v[138:139] op_sel_hi:[1,0]
	v_pk_mul_f32 v[120:121], v[120:121], v[138:139] op_sel_hi:[1,0]
	v_pk_mul_f32 v[126:127], v[126:127], v[138:139] op_sel_hi:[1,0]
	v_pk_mul_f32 v[128:129], v[128:129], v[138:139] op_sel_hi:[1,0]
	v_pk_mul_f32 v[122:123], v[122:123], v[138:139] op_sel_hi:[1,0]
	v_pk_mul_f32 v[124:125], v[124:125], v[138:139] op_sel_hi:[1,0]
	v_cvt_pk_bf16_f32 v146, v114, v115
	v_cvt_pk_bf16_f32 v147, v116, v117
	v_cvt_pk_bf16_f32 v148, v118, v119
	v_cvt_pk_bf16_f32 v149, v120, v121
	v_cvt_pk_bf16_f32 v150, v126, v127
	v_cvt_pk_bf16_f32 v151, v128, v129
	v_cvt_pk_bf16_f32 v152, v122, v123
	v_cvt_pk_bf16_f32 v153, v124, v125
	s_nop 1
	v_permlane16_swap_b32_e32 v146, v148
	v_permlane16_swap_b32_e32 v147, v149
	v_permlane16_swap_b32_e32 v150, v152
	v_permlane16_swap_b32_e32 v151, v153
	global_store_dwordx4 v[134:135], v[146:149], off
	global_store_dwordx4 v[134:135], v[150:153], off offset:256
	v_lshl_add_u64 v[134:135], v[134:135], 0, s[12:13]
	v_pk_mul_f32 v[98:99], v[98:99], v[138:139] op_sel:[0,1] op_sel_hi:[1,1]
	v_pk_mul_f32 v[100:101], v[100:101], v[138:139] op_sel:[0,1] op_sel_hi:[1,1]
	v_pk_mul_f32 v[102:103], v[102:103], v[138:139] op_sel:[0,1] op_sel_hi:[1,1]
	v_pk_mul_f32 v[104:105], v[104:105], v[138:139] op_sel:[0,1] op_sel_hi:[1,1]
	v_pk_mul_f32 v[110:111], v[110:111], v[138:139] op_sel:[0,1] op_sel_hi:[1,1]
	v_pk_mul_f32 v[112:113], v[112:113], v[138:139] op_sel:[0,1] op_sel_hi:[1,1]
	v_pk_mul_f32 v[106:107], v[106:107], v[138:139] op_sel:[0,1] op_sel_hi:[1,1]
	v_pk_mul_f32 v[108:109], v[108:109], v[138:139] op_sel:[0,1] op_sel_hi:[1,1]
	v_cvt_pk_bf16_f32 v154, v98, v99
	v_cvt_pk_bf16_f32 v155, v100, v101
	v_cvt_pk_bf16_f32 v156, v102, v103
	v_cvt_pk_bf16_f32 v157, v104, v105
	v_cvt_pk_bf16_f32 v158, v110, v111
	v_cvt_pk_bf16_f32 v159, v112, v113
	v_cvt_pk_bf16_f32 v160, v106, v107
	v_cvt_pk_bf16_f32 v161, v108, v109
	s_nop 1
	v_permlane16_swap_b32_e32 v154, v156
	v_permlane16_swap_b32_e32 v155, v157
	v_permlane16_swap_b32_e32 v158, v160
	v_permlane16_swap_b32_e32 v159, v161
	global_store_dwordx4 v[134:135], v[154:157], off
	global_store_dwordx4 v[134:135], v[158:161], off offset:256
	v_lshl_add_u64 v[134:135], v[134:135], 0, s[12:13]
	v_pk_mul_f32 v[82:83], v[82:83], v[140:141] op_sel_hi:[1,0]
	v_pk_mul_f32 v[84:85], v[84:85], v[140:141] op_sel_hi:[1,0]
	v_pk_mul_f32 v[86:87], v[86:87], v[140:141] op_sel_hi:[1,0]
	v_pk_mul_f32 v[88:89], v[88:89], v[140:141] op_sel_hi:[1,0]
	v_pk_mul_f32 v[94:95], v[94:95], v[140:141] op_sel_hi:[1,0]
	v_pk_mul_f32 v[96:97], v[96:97], v[140:141] op_sel_hi:[1,0]
	v_pk_mul_f32 v[90:91], v[90:91], v[140:141] op_sel_hi:[1,0]
	v_pk_mul_f32 v[92:93], v[92:93], v[140:141] op_sel_hi:[1,0]
	v_cvt_pk_bf16_f32 v146, v82, v83
	v_cvt_pk_bf16_f32 v147, v84, v85
	v_cvt_pk_bf16_f32 v148, v86, v87
	v_cvt_pk_bf16_f32 v149, v88, v89
	v_cvt_pk_bf16_f32 v150, v94, v95
	v_cvt_pk_bf16_f32 v151, v96, v97
	v_cvt_pk_bf16_f32 v152, v90, v91
	v_cvt_pk_bf16_f32 v153, v92, v93
	s_nop 1
	v_permlane16_swap_b32_e32 v146, v148
	v_permlane16_swap_b32_e32 v147, v149
	v_permlane16_swap_b32_e32 v150, v152
	v_permlane16_swap_b32_e32 v151, v153
	global_store_dwordx4 v[134:135], v[146:149], off
	global_store_dwordx4 v[134:135], v[150:153], off offset:256
	v_lshl_add_u64 v[134:135], v[134:135], 0, s[12:13]
	v_pk_mul_f32 v[66:67], v[66:67], v[140:141] op_sel:[0,1] op_sel_hi:[1,1]
	v_pk_mul_f32 v[68:69], v[68:69], v[140:141] op_sel:[0,1] op_sel_hi:[1,1]
	v_pk_mul_f32 v[70:71], v[70:71], v[140:141] op_sel:[0,1] op_sel_hi:[1,1]
	v_pk_mul_f32 v[72:73], v[72:73], v[140:141] op_sel:[0,1] op_sel_hi:[1,1]
	v_pk_mul_f32 v[78:79], v[78:79], v[140:141] op_sel:[0,1] op_sel_hi:[1,1]
	v_pk_mul_f32 v[80:81], v[80:81], v[140:141] op_sel:[0,1] op_sel_hi:[1,1]
	v_pk_mul_f32 v[74:75], v[74:75], v[140:141] op_sel:[0,1] op_sel_hi:[1,1]
	v_pk_mul_f32 v[76:77], v[76:77], v[140:141] op_sel:[0,1] op_sel_hi:[1,1]
	v_cvt_pk_bf16_f32 v154, v66, v67
	v_cvt_pk_bf16_f32 v155, v68, v69
	v_cvt_pk_bf16_f32 v156, v70, v71
	v_cvt_pk_bf16_f32 v157, v72, v73
	v_cvt_pk_bf16_f32 v158, v78, v79
	v_cvt_pk_bf16_f32 v159, v80, v81
	v_cvt_pk_bf16_f32 v160, v74, v75
	v_cvt_pk_bf16_f32 v161, v76, v77
	s_nop 1
	v_permlane16_swap_b32_e32 v154, v156
	v_permlane16_swap_b32_e32 v155, v157
	v_permlane16_swap_b32_e32 v158, v160
; #define SCHED __builtin_amdgcn_sched_barrier(0)
; template <int EPI>
; __device__ __forceinline__ void gemm_tile(const GemmArgs& g, int brow, int bcol, int parity, bool first, bool nvalid, int nbrow, int nbcol) {
;     ...
;     } else {
;       _Pragma("unroll") for (int ai = 0; ai < 2; ++ai) _Pragma("unroll") for (int bj = 0; bj < 2; ++bj) {
;         SCHED;
;         _Pragma("unroll") for (int m = 0; m < 4; ++m) _Pragma("unroll") for (int j = 0; j < 4; ++j) {
;           const float rs = rstd_s[lrow0 + ai * HALF + m * 16 + fq * 4 + j];
;           _Pragma("unroll") for (int n = 0; n < 2; ++n) W_WRITE(m, n, j, acc[ai][bj][m][n][j] * rs);
;         }
;         bfu* dst = g.outb + (long)(wrow0 + ai * HALF) * g.ldo + wcol0 + bj * HALF;
;         W_STORE_BF16(dst, g.ldo);
;       }
	v_permlane16_swap_b32_e32 v159, v161
	global_store_dwordx4 v[134:135], v[154:157], off
	global_store_dwordx4 v[134:135], v[158:161], off offset:256
	v_lshl_add_u64 v[134:135], v[134:135], 0, s[14:15]
	v_pk_mul_f32 v[50:51], v[50:51], v[142:143] op_sel_hi:[1,0]
	v_pk_mul_f32 v[52:53], v[52:53], v[142:143] op_sel_hi:[1,0]
	v_pk_mul_f32 v[54:55], v[54:55], v[142:143] op_sel_hi:[1,0]
	v_pk_mul_f32 v[56:57], v[56:57], v[142:143] op_sel_hi:[1,0]
	v_pk_mul_f32 v[62:63], v[62:63], v[142:143] op_sel_hi:[1,0]
	v_pk_mul_f32 v[64:65], v[64:65], v[142:143] op_sel_hi:[1,0]
	v_pk_mul_f32 v[58:59], v[58:59], v[142:143] op_sel_hi:[1,0]
	v_pk_mul_f32 v[60:61], v[60:61], v[142:143] op_sel_hi:[1,0]
	v_cvt_pk_bf16_f32 v146, v50, v51
	v_cvt_pk_bf16_f32 v147, v52, v53
	v_cvt_pk_bf16_f32 v148, v54, v55
	v_cvt_pk_bf16_f32 v149, v56, v57
	v_cvt_pk_bf16_f32 v150, v62, v63
	v_cvt_pk_bf16_f32 v151, v64, v65
	v_cvt_pk_bf16_f32 v152, v58, v59
	v_cvt_pk_bf16_f32 v153, v60, v61
	s_nop 1
	v_permlane16_swap_b32_e32 v146, v148
	v_permlane16_swap_b32_e32 v147, v149
	v_permlane16_swap_b32_e32 v150, v152
	v_permlane16_swap_b32_e32 v151, v153
	global_store_dwordx4 v[134:135], v[146:149], off
	global_store_dwordx4 v[134:135], v[150:153], off offset:256
	v_lshl_add_u64 v[134:135], v[134:135], 0, s[12:13]
	v_pk_mul_f32 v[34:35], v[34:35], v[142:143] op_sel:[0,1] op_sel_hi:[1,1]
	v_pk_mul_f32 v[36:37], v[36:37], v[142:143] op_sel:[0,1] op_sel_hi:[1,1]
	v_pk_mul_f32 v[38:39], v[38:39], v[142:143] op_sel:[0,1] op_sel_hi:[1,1]
	v_pk_mul_f32 v[40:41], v[40:41], v[142:143] op_sel:[0,1] op_sel_hi:[1,1]
	v_pk_mul_f32 v[46:47], v[46:47], v[142:143] op_sel:[0,1] op_sel_hi:[1,1]
	v_pk_mul_f32 v[48:49], v[48:49], v[142:143] op_sel:[0,1] op_sel_hi:[1,1]
	v_pk_mul_f32 v[42:43], v[42:43], v[142:143] op_sel:[0,1] op_sel_hi:[1,1]
	v_pk_mul_f32 v[44:45], v[44:45], v[142:143] op_sel:[0,1] op_sel_hi:[1,1]
	v_cvt_pk_bf16_f32 v154, v34, v35
	v_cvt_pk_bf16_f32 v155, v36, v37
	v_cvt_pk_bf16_f32 v156, v38, v39
	v_cvt_pk_bf16_f32 v157, v40, v41
	v_cvt_pk_bf16_f32 v158, v46, v47
	v_cvt_pk_bf16_f32 v159, v48, v49
	v_cvt_pk_bf16_f32 v160, v42, v43
	v_cvt_pk_bf16_f32 v161, v44, v45
	s_nop 1
	v_permlane16_swap_b32_e32 v154, v156
	v_permlane16_swap_b32_e32 v155, v157
	v_permlane16_swap_b32_e32 v158, v160
	v_permlane16_swap_b32_e32 v159, v161
	global_store_dwordx4 v[134:135], v[154:157], off
	global_store_dwordx4 v[134:135], v[158:161], off offset:256
	v_lshl_add_u64 v[134:135], v[134:135], 0, s[12:13]
	v_pk_mul_f32 v[18:19], v[18:19], v[144:145] op_sel_hi:[1,0]
	v_pk_mul_f32 v[20:21], v[20:21], v[144:145] op_sel_hi:[1,0]
	v_pk_mul_f32 v[22:23], v[22:23], v[144:145] op_sel_hi:[1,0]
	v_pk_mul_f32 v[24:25], v[24:25], v[144:145] op_sel_hi:[1,0]
	v_pk_mul_f32 v[30:31], v[30:31], v[144:145] op_sel_hi:[1,0]
	v_pk_mul_f32 v[32:33], v[32:33], v[144:145] op_sel_hi:[1,0]
	v_pk_mul_f32 v[26:27], v[26:27], v[144:145] op_sel_hi:[1,0]
	v_pk_mul_f32 v[28:29], v[28:29], v[144:145] op_sel_hi:[1,0]
	v_cvt_pk_bf16_f32 v146, v18, v19
	v_cvt_pk_bf16_f32 v147, v20, v21
	v_cvt_pk_bf16_f32 v148, v22, v23
	v_cvt_pk_bf16_f32 v149, v24, v25
	v_cvt_pk_bf16_f32 v150, v30, v31
	v_cvt_pk_bf16_f32 v151, v32, v33
	v_cvt_pk_bf16_f32 v152, v26, v27
	v_cvt_pk_bf16_f32 v153, v28, v29
	s_nop 1
	v_permlane16_swap_b32_e32 v146, v148
	v_permlane16_swap_b32_e32 v147, v149
	v_permlane16_swap_b32_e32 v150, v152
	v_permlane16_swap_b32_e32 v151, v153
	global_store_dwordx4 v[134:135], v[146:149], off
	global_store_dwordx4 v[134:135], v[150:153], off offset:256
	v_lshl_add_u64 v[134:135], v[134:135], 0, s[12:13]
	v_pk_mul_f32 v[2:3], v[2:3], v[144:145] op_sel:[0,1] op_sel_hi:[1,1]
	v_pk_mul_f32 v[4:5], v[4:5], v[144:145] op_sel:[0,1] op_sel_hi:[1,1]
	v_pk_mul_f32 v[6:7], v[6:7], v[144:145] op_sel:[0,1] op_sel_hi:[1,1]
	v_pk_mul_f32 v[8:9], v[8:9], v[144:145] op_sel:[0,1] op_sel_hi:[1,1]
	v_pk_mul_f32 v[14:15], v[14:15], v[144:145] op_sel:[0,1] op_sel_hi:[1,1]
	v_pk_mul_f32 v[16:17], v[16:17], v[144:145] op_sel:[0,1] op_sel_hi:[1,1]
	v_pk_mul_f32 v[10:11], v[10:11], v[144:145] op_sel:[0,1] op_sel_hi:[1,1]
	v_pk_mul_f32 v[12:13], v[12:13], v[144:145] op_sel:[0,1] op_sel_hi:[1,1]
	v_cvt_pk_bf16_f32 v154, v2, v3
	v_cvt_pk_bf16_f32 v155, v4, v5
	v_cvt_pk_bf16_f32 v156, v6, v7
	v_cvt_pk_bf16_f32 v157, v8, v9
	v_cvt_pk_bf16_f32 v158, v14, v15
	v_cvt_pk_bf16_f32 v159, v16, v17
	v_cvt_pk_bf16_f32 v160, v10, v11
	v_cvt_pk_bf16_f32 v161, v12, v13
	s_nop 1
	v_permlane16_swap_b32_e32 v154, v156
	v_permlane16_swap_b32_e32 v155, v157
	v_permlane16_swap_b32_e32 v158, v160
	v_permlane16_swap_b32_e32 v159, v161
	global_store_dwordx4 v[134:135], v[154:157], off
	global_store_dwordx4 v[134:135], v[158:161], off offset:256
	s_branch .Lswa_epi_done
; #define GPTR(T, ptr) ((__attribute__((address_space(1))) T*)(ptr))
; template <int EPI>
; __device__ __forceinline__ void gemm_tile(const GemmArgs& g, int brow, int bcol, int parity, bool first, bool nvalid, int nbrow, int nbcol) {
;     ...
;       _Pragma("unroll") for (int ai = 0; ai < 2; ++ai) _Pragma("unroll") for (int mh = 0; mh < 2; ++mh) {
;         SCHED;
;         _Pragma("unroll") for (int mm = 0; mm < 2; ++mm) _Pragma("unroll") for (int j = 0; j < 4; ++j) {
;           const int m = mh * 2 + mm;
;           const float rs = rstd_s[lrow0 + ai * HALF + m * 16 + fq * 4 + j] * qs;
;           _Pragma("unroll") for (int n = 0; n < 2; ++n) {
;             Wa[(mm * 16 + fq * 4 + j) * 36 + n * 16 + fr] = acc[ai][0][m][n][j] * rs;
;             Wb[(mm * 16 + fq * 4 + j) * 36 + n * 16 + fr] = acc[ai][1][m][n][j] * rs;
;           }
;         }
;         f32x4 cv[2][2], sv[2][2];
;         _Pragma("unroll") for (int ps = 0; ps < 2; ++ps) {
;           const int t = (wrow0 + ai * HALF + mh * 32 + ps * 16 + (lane >> 2)) & (TSEQ - 1);
;           const int dcol = dd0 + (lane & 3) * 8;
;           cv[ps][0] = *GPTR(const f32x4, g.rope + t * 64 + dcol); cv[ps][1] = *GPTR(const f32x4, g.rope + t * 64 + dcol + 4);
;           sv[ps][0] = *GPTR(const f32x4, g.rope + TSEQ * 64 + t * 64 + dcol); sv[ps][1] = *GPTR(const f32x4, g.rope + TSEQ * 64 + t * 64 + dcol + 4);
;         }
;         _Pragma("unroll") for (int ps = 0; ps < 2; ++ps) {
;           const int r_ = ps * 16 + (lane >> 2), c_ = (lane & 3) * 8;
;           const int grow = wrow0 + ai * HALF + mh * 32 + r_;
;           const float4 xa0 = *(const float4*)(Wa + r_ * 36 + c_), xa1 = *(const float4*)(Wa + r_ * 36 + c_ + 4);
;           const float4 xb0 = *(const float4*)(Wb + r_ * 36 + c_), xb1 = *(const float4*)(Wb + r_ * 36 + c_ + 4);
;           const f32x4 c0v = cv[ps][0], c1v = cv[ps][1], s0v = sv[ps][0], s1v = sv[ps][1];
;           u32x4 y1, y2;
;           y1[0] = pack2(xa0.x * c0v[0] - xb0.x * s0v[0], xa0.y * c0v[1] - xb0.y * s0v[1]);
;           y1[1] = pack2(xa0.z * c0v[2] - xb0.z * s0v[2], xa0.w * c0v[3] - xb0.w * s0v[3]);
;           y1[2] = pack2(xa1.x * c1v[0] - xb1.x * s1v[0], xa1.y * c1v[1] - xb1.y * s1v[1]);
;           y1[3] = pack2(xa1.z * c1v[2] - xb1.z * s1v[2], xa1.w * c1v[3] - xb1.w * s1v[3]);
;           y2[0] = pack2(xa0.x * s0v[0] + xb0.x * c0v[0], xa0.y * s0v[1] + xb0.y * c0v[1]);
.Lswa_epi_rope:
	v_readlane_b32 s22, v252, 22
	v_readlane_b32 s23, v252, 23
	s_mov_b32 s2, 0x3db504f3
	s_cmpk_lt_i32 s38, 0x600
	s_cselect_b32 s2, s2, 1.0
	s_add_u32 s24, s22, 0x100000
	s_addc_u32 s25, s23, 0
	v_mul_f32_e32 v138, s2, v138
	v_mul_f32_e32 v139, s2, v139
	v_mul_f32_e32 v140, s2, v140
	v_mul_f32_e32 v141, s2, v141
	v_mul_f32_e32 v142, s2, v142
	v_mul_f32_e32 v143, s2, v143
	v_mul_f32_e32 v144, s2, v144
	v_mul_f32_e32 v145, s2, v145
	s_and_b32 s3, s33, 0x80
	s_mov_b32 s13, 0
	s_mov_b32 s12, s3
	v_lshl_add_u64 v[134:135], v[134:135], 0, s[12:13]
	s_mov_b64 s[12:13], 0x24000
	v_and_b32_e32 v166, 0xfff, v136
	v_lshlrev_b32_e32 v166, 8, v166
	v_lshl_add_u32 v166, v132, 4, v166
	s_and_b32 s3, s33, 0x40
	s_lshl_b32 s3, s3, 1
	v_add_u32_e32 v166, s3, v166
	global_load_dwordx4 v[170:173], v166, s[22:23]
	global_load_dwordx4 v[174:177], v166, s[22:23] offset:64
	global_load_dwordx4 v[178:181], v166, s[24:25]
	global_load_dwordx4 v[182:185], v166, s[24:25] offset:64
	v_add_u32_e32 v167, 0x1000, v166
	global_load_dwordx4 v[228:231], v167, s[22:23]
	global_load_dwordx4 v[232:235], v167, s[22:23] offset:64
	global_load_dwordx4 v[236:239], v167, s[24:25]
	global_load_dwordx4 v[240:243], v167, s[24:25] offset:64
	v_pk_mul_f32 v[114:115], v[114:115], v[138:139] op_sel_hi:[1,0]
	v_pk_mul_f32 v[116:117], v[116:117], v[138:139] op_sel_hi:[1,0]
	v_pk_mul_f32 v[118:119], v[118:119], v[138:139] op_sel_hi:[1,0]
	v_pk_mul_f32 v[120:121], v[120:121], v[138:139] op_sel_hi:[1,0]
	v_pk_mul_f32 v[126:127], v[126:127], v[138:139] op_sel_hi:[1,0]
	v_pk_mul_f32 v[128:129], v[128:129], v[138:139] op_sel_hi:[1,0]
	v_pk_mul_f32 v[122:123], v[122:123], v[138:139] op_sel_hi:[1,0]
	v_pk_mul_f32 v[124:125], v[124:125], v[138:139] op_sel_hi:[1,0]
	s_waitcnt vmcnt(4)
	v_pk_mul_f32 v[162:163], v[126:127], v[178:179]
	v_pk_mul_f32 v[164:165], v[126:127], v[170:171]
	v_pk_fma_f32 v[126:127], v[114:115], v[178:179], v[164:165]
	v_pk_fma_f32 v[114:115], v[114:115], v[170:171], v[162:163] neg_lo:[0,0,1] neg_hi:[0,0,1]
	v_pk_mul_f32 v[162:163], v[128:129], v[180:181]
	v_pk_mul_f32 v[164:165], v[128:129], v[172:173]
	v_pk_fma_f32 v[128:129], v[116:117], v[180:181], v[164:165]
	v_pk_fma_f32 v[116:117], v[116:117], v[172:173], v[162:163] neg_lo:[0,0,1] neg_hi:[0,0,1]
	v_pk_mul_f32 v[162:163], v[122:123], v[182:183]
	v_pk_mul_f32 v[164:165], v[122:123], v[174:175]
	v_pk_fma_f32 v[122:123], v[118:119], v[182:183], v[164:165]
	v_pk_fma_f32 v[118:119], v[118:119], v[174:175], v[162:163] neg_lo:[0,0,1] neg_hi:[0,0,1]
	v_pk_mul_f32 v[162:163], v[124:125], v[184:185]
	v_pk_mul_f32 v[164:165], v[124:125], v[176:177]
	v_pk_fma_f32 v[124:125], v[120:121], v[184:185], v[164:165]
	v_pk_fma_f32 v[120:121], v[120:121], v[176:177], v[162:163] neg_lo:[0,0,1] neg_hi:[0,0,1]
	v_cvt_pk_bf16_f32 v146, v114, v115
	v_cvt_pk_bf16_f32 v147, v116, v117
	v_cvt_pk_bf16_f32 v148, v118, v119
	v_cvt_pk_bf16_f32 v149, v120, v121
	v_cvt_pk_bf16_f32 v150, v126, v127
	v_cvt_pk_bf16_f32 v151, v128, v129
	v_cvt_pk_bf16_f32 v152, v122, v123
	v_cvt_pk_bf16_f32 v153, v124, v125
	s_nop 1
	v_permlane16_swap_b32_e32 v146, v148
	v_permlane16_swap_b32_e32 v147, v149
	v_permlane16_swap_b32_e32 v150, v152
	v_permlane16_swap_b32_e32 v151, v153
	global_store_dwordx4 v[134:135], v[146:149], off
	global_store_dwordx4 v[134:135], v[150:153], off offset:128
	v_lshl_add_u64 v[134:135], v[134:135], 0, s[12:13]
	v_add_u32_e32 v167, 0x2000, v166
	global_load_dwordx4 v[170:173], v167, s[22:23]
	global_load_dwordx4 v[174:177], v167, s[22:23] offset:64
	global_load_dwordx4 v[178:181], v167, s[24:25]
	global_load_dwordx4 v[182:185], v167, s[24:25] offset:64
	v_pk_mul_f32 v[98:99], v[98:99], v[138:139] op_sel:[0,1] op_sel_hi:[1,1]
	v_pk_mul_f32 v[100:101], v[100:101], v[138:139] op_sel:[0,1] op_sel_hi:[1,1]
	v_pk_mul_f32 v[102:103], v[102:103], v[138:139] op_sel:[0,1] op_sel_hi:[1,1]
	v_pk_mul_f32 v[104:105], v[104:105], v[138:139] op_sel:[0,1] op_sel_hi:[1,1]
	v_pk_mul_f32 v[110:111], v[110:111], v[138:139] op_sel:[0,1] op_sel_hi:[1,1]
	v_pk_mul_f32 v[112:113], v[112:113], v[138:139] op_sel:[0,1] op_sel_hi:[1,1]
	v_pk_mul_f32 v[106:107], v[106:107], v[138:139] op_sel:[0,1] op_sel_hi:[1,1]
	v_pk_mul_f32 v[108:109], v[108:109], v[138:139] op_sel:[0,1] op_sel_hi:[1,1]
	s_waitcnt vmcnt(6)
	v_pk_mul_f32 v[162:163], v[110:111], v[236:237]
	v_pk_mul_f32 v[164:165], v[110:111], v[228:229]
	v_pk_fma_f32 v[110:111], v[98:99], v[236:237], v[164:165]
	v_pk_fma_f32 v[98:99], v[98:99], v[228:229], v[162:163] neg_lo:[0,0,1] neg_hi:[0,0,1]
	v_pk_mul_f32 v[162:163], v[112:113], v[238:239]
	v_pk_mul_f32 v[164:165], v[112:113], v[230:231]
	v_pk_fma_f32 v[112:113], v[100:101], v[238:239], v[164:165]
	v_pk_fma_f32 v[100:101], v[100:101], v[230:231], v[162:163] neg_lo:[0,0,1] neg_hi:[0,0,1]
	v_pk_mul_f32 v[162:163], v[106:107], v[240:241]
	v_pk_mul_f32 v[164:165], v[106:107], v[232:233]
	v_pk_fma_f32 v[106:107], v[102:103], v[240:241], v[164:165]
	v_pk_fma_f32 v[102:103], v[102:103], v[232:233], v[162:163] neg_lo:[0,0,1] neg_hi:[0,0,1]
	v_pk_mul_f32 v[162:163], v[108:109], v[242:243]
	v_pk_mul_f32 v[164:165], v[108:109], v[234:235]
	v_pk_fma_f32 v[108:109], v[104:105], v[242:243], v[164:165]
	v_pk_fma_f32 v[104:105], v[104:105], v[234:235], v[162:163] neg_lo:[0,0,1] neg_hi:[0,0,1]
	v_cvt_pk_bf16_f32 v154, v98, v99
	v_cvt_pk_bf16_f32 v155, v100, v101
	v_cvt_pk_bf16_f32 v156, v102, v103
	v_cvt_pk_bf16_f32 v157, v104, v105
	v_cvt_pk_bf16_f32 v158, v110, v111
	v_cvt_pk_bf16_f32 v159, v112, v113
	v_cvt_pk_bf16_f32 v160, v106, v107
	v_cvt_pk_bf16_f32 v161, v108, v109
	s_nop 1
	v_permlane16_swap_b32_e32 v154, v156
	v_permlane16_swap_b32_e32 v155, v157
	v_permlane16_swap_b32_e32 v158, v160
	v_permlane16_swap_b32_e32 v159, v161
	global_store_dwordx4 v[134:135], v[154:157], off
	global_store_dwordx4 v[134:135], v[158:161], off offset:128
	v_lshl_add_u64 v[134:135], v[134:135], 0, s[12:13]
	v_add_u32_e32 v167, 0x3000, v166
	global_load_dwordx4 v[228:231], v167, s[22:23]
	global_load_dwordx4 v[232:235], v167, s[22:23] offset:64
	global_load_dwordx4 v[236:239], v167, s[24:25]
	global_load_dwordx4 v[240:243], v167, s[24:25] offset:64
	v_pk_mul_f32 v[82:83], v[82:83], v[140:141] op_sel_hi:[1,0]
	v_pk_mul_f32 v[84:85], v[84:85], v[140:141] op_sel_hi:[1,0]
	v_pk_mul_f32 v[86:87], v[86:87], v[140:141] op_sel_hi:[1,0]
	v_pk_mul_f32 v[88:89], v[88:89], v[140:141] op_sel_hi:[1,0]
	v_pk_mul_f32 v[94:95], v[94:95], v[140:141] op_sel_hi:[1,0]
	v_pk_mul_f32 v[96:97], v[96:97], v[140:141] op_sel_hi:[1,0]
	v_pk_mul_f32 v[90:91], v[90:91], v[140:141] op_sel_hi:[1,0]
	v_pk_mul_f32 v[92:93], v[92:93], v[140:141] op_sel_hi:[1,0]
	s_waitcnt vmcnt(6)
; #define GPTR(T, ptr) ((__attribute__((address_space(1))) T*)(ptr))
; template <int EPI>
; __device__ __forceinline__ void gemm_tile(const GemmArgs& g, int brow, int bcol, int parity, bool first, bool nvalid, int nbrow, int nbcol) {
;     ...
;       _Pragma("unroll") for (int ai = 0; ai < 2; ++ai) _Pragma("unroll") for (int mh = 0; mh < 2; ++mh) {
;         SCHED;
;         _Pragma("unroll") for (int mm = 0; mm < 2; ++mm) _Pragma("unroll") for (int j = 0; j < 4; ++j) {
;           const int m = mh * 2 + mm;
;           const float rs = rstd_s[lrow0 + ai * HALF + m * 16 + fq * 4 + j] * qs;
;           _Pragma("unroll") for (int n = 0; n < 2; ++n) {
;             Wa[(mm * 16 + fq * 4 + j) * 36 + n * 16 + fr] = acc[ai][0][m][n][j] * rs;
;             Wb[(mm * 16 + fq * 4 + j) * 36 + n * 16 + fr] = acc[ai][1][m][n][j] * rs;
;           }
;         }
;         f32x4 cv[2][2], sv[2][2];
;         _Pragma("unroll") for (int ps = 0; ps < 2; ++ps) {
;           const int t = (wrow0 + ai * HALF + mh * 32 + ps * 16 + (lane >> 2)) & (TSEQ - 1);
;           const int dcol = dd0 + (lane & 3) * 8;
;           cv[ps][0] = *GPTR(const f32x4, g.rope + t * 64 + dcol); cv[ps][1] = *GPTR(const f32x4, g.rope + t * 64 + dcol + 4);
;           sv[ps][0] = *GPTR(const f32x4, g.rope + TSEQ * 64 + t * 64 + dcol); sv[ps][1] = *GPTR(const f32x4, g.rope + TSEQ * 64 + t * 64 + dcol + 4);
;         }
;         _Pragma("unroll") for (int ps = 0; ps < 2; ++ps) {
;           const int r_ = ps * 16 + (lane >> 2), c_ = (lane & 3) * 8;
;           const int grow = wrow0 + ai * HALF + mh * 32 + r_;
;           const float4 xa0 = *(const float4*)(Wa + r_ * 36 + c_), xa1 = *(const float4*)(Wa + r_ * 36 + c_ + 4);
;           const float4 xb0 = *(const float4*)(Wb + r_ * 36 + c_), xb1 = *(const float4*)(Wb + r_ * 36 + c_ + 4);
;           const f32x4 c0v = cv[ps][0], c1v = cv[ps][1], s0v = sv[ps][0], s1v = sv[ps][1];
;           u32x4 y1, y2;
;           y1[0] = pack2(xa0.x * c0v[0] - xb0.x * s0v[0], xa0.y * c0v[1] - xb0.y * s0v[1]);
;           y1[1] = pack2(xa0.z * c0v[2] - xb0.z * s0v[2], xa0.w * c0v[3] - xb0.w * s0v[3]);
;           y1[2] = pack2(xa1.x * c1v[0] - xb1.x * s1v[0], xa1.y * c1v[1] - xb1.y * s1v[1]);
;           y1[3] = pack2(xa1.z * c1v[2] - xb1.z * s1v[2], xa1.w * c1v[3] - xb1.w * s1v[3]);
;           y2[0] = pack2(xa0.x * s0v[0] + xb0.x * c0v[0], xa0.y * s0v[1] + xb0.y * c0v[1]);
	v_pk_mul_f32 v[162:163], v[94:95], v[178:179]
	v_pk_mul_f32 v[164:165], v[94:95], v[170:171]
	v_pk_fma_f32 v[94:95], v[82:83], v[178:179], v[164:165]
	v_pk_fma_f32 v[82:83], v[82:83], v[170:171], v[162:163] neg_lo:[0,0,1] neg_hi:[0,0,1]
	v_pk_mul_f32 v[162:163], v[96:97], v[180:181]
	v_pk_mul_f32 v[164:165], v[96:97], v[172:173]
	v_pk_fma_f32 v[96:97], v[84:85], v[180:181], v[164:165]
	v_pk_fma_f32 v[84:85], v[84:85], v[172:173], v[162:163] neg_lo:[0,0,1] neg_hi:[0,0,1]
	v_pk_mul_f32 v[162:163], v[90:91], v[182:183]
	v_pk_mul_f32 v[164:165], v[90:91], v[174:175]
	v_pk_fma_f32 v[90:91], v[86:87], v[182:183], v[164:165]
	v_pk_fma_f32 v[86:87], v[86:87], v[174:175], v[162:163] neg_lo:[0,0,1] neg_hi:[0,0,1]
	v_pk_mul_f32 v[162:163], v[92:93], v[184:185]
	v_pk_mul_f32 v[164:165], v[92:93], v[176:177]
	v_pk_fma_f32 v[92:93], v[88:89], v[184:185], v[164:165]
	v_pk_fma_f32 v[88:89], v[88:89], v[176:177], v[162:163] neg_lo:[0,0,1] neg_hi:[0,0,1]
	v_cvt_pk_bf16_f32 v146, v82, v83
	v_cvt_pk_bf16_f32 v147, v84, v85
	v_cvt_pk_bf16_f32 v148, v86, v87
	v_cvt_pk_bf16_f32 v149, v88, v89
	v_cvt_pk_bf16_f32 v150, v94, v95
	v_cvt_pk_bf16_f32 v151, v96, v97
	v_cvt_pk_bf16_f32 v152, v90, v91
	v_cvt_pk_bf16_f32 v153, v92, v93
	s_nop 1
	v_permlane16_swap_b32_e32 v146, v148
	v_permlane16_swap_b32_e32 v147, v149
	v_permlane16_swap_b32_e32 v150, v152
	v_permlane16_swap_b32_e32 v151, v153
	global_store_dwordx4 v[134:135], v[146:149], off
	global_store_dwordx4 v[134:135], v[150:153], off offset:128
	v_lshl_add_u64 v[134:135], v[134:135], 0, s[12:13]
	v_add_u32_e32 v167, 0x8000, v166
	global_load_dwordx4 v[170:173], v167, s[22:23]
	global_load_dwordx4 v[174:177], v167, s[22:23] offset:64
	global_load_dwordx4 v[178:181], v167, s[24:25]
	global_load_dwordx4 v[182:185], v167, s[24:25] offset:64
	v_pk_mul_f32 v[66:67], v[66:67], v[140:141] op_sel:[0,1] op_sel_hi:[1,1]
	v_pk_mul_f32 v[68:69], v[68:69], v[140:141] op_sel:[0,1] op_sel_hi:[1,1]
	v_pk_mul_f32 v[70:71], v[70:71], v[140:141] op_sel:[0,1] op_sel_hi:[1,1]
	v_pk_mul_f32 v[72:73], v[72:73], v[140:141] op_sel:[0,1] op_sel_hi:[1,1]
	v_pk_mul_f32 v[78:79], v[78:79], v[140:141] op_sel:[0,1] op_sel_hi:[1,1]
	v_pk_mul_f32 v[80:81], v[80:81], v[140:141] op_sel:[0,1] op_sel_hi:[1,1]
	v_pk_mul_f32 v[74:75], v[74:75], v[140:141] op_sel:[0,1] op_sel_hi:[1,1]
	v_pk_mul_f32 v[76:77], v[76:77], v[140:141] op_sel:[0,1] op_sel_hi:[1,1]
	s_waitcnt vmcnt(6)
	v_pk_mul_f32 v[162:163], v[78:79], v[236:237]
	v_pk_mul_f32 v[164:165], v[78:79], v[228:229]
	v_pk_fma_f32 v[78:79], v[66:67], v[236:237], v[164:165]
	v_pk_fma_f32 v[66:67], v[66:67], v[228:229], v[162:163] neg_lo:[0,0,1] neg_hi:[0,0,1]
	v_pk_mul_f32 v[162:163], v[80:81], v[238:239]
	v_pk_mul_f32 v[164:165], v[80:81], v[230:231]
	v_pk_fma_f32 v[80:81], v[68:69], v[238:239], v[164:165]
	v_pk_fma_f32 v[68:69], v[68:69], v[230:231], v[162:163] neg_lo:[0,0,1] neg_hi:[0,0,1]
	v_pk_mul_f32 v[162:163], v[74:75], v[240:241]
	v_pk_mul_f32 v[164:165], v[74:75], v[232:233]
	v_pk_fma_f32 v[74:75], v[70:71], v[240:241], v[164:165]
	v_pk_fma_f32 v[70:71], v[70:71], v[232:233], v[162:163] neg_lo:[0,0,1] neg_hi:[0,0,1]
	v_pk_mul_f32 v[162:163], v[76:77], v[242:243]
	v_pk_mul_f32 v[164:165], v[76:77], v[234:235]
	v_pk_fma_f32 v[76:77], v[72:73], v[242:243], v[164:165]
	v_pk_fma_f32 v[72:73], v[72:73], v[234:235], v[162:163] neg_lo:[0,0,1] neg_hi:[0,0,1]
	v_cvt_pk_bf16_f32 v154, v66, v67
	v_cvt_pk_bf16_f32 v155, v68, v69
	v_cvt_pk_bf16_f32 v156, v70, v71
	v_cvt_pk_bf16_f32 v157, v72, v73
	v_cvt_pk_bf16_f32 v158, v78, v79
	v_cvt_pk_bf16_f32 v159, v80, v81
	v_cvt_pk_bf16_f32 v160, v74, v75
	v_cvt_pk_bf16_f32 v161, v76, v77
	s_nop 1
	v_permlane16_swap_b32_e32 v154, v156
	v_permlane16_swap_b32_e32 v155, v157
	v_permlane16_swap_b32_e32 v158, v160
	v_permlane16_swap_b32_e32 v159, v161
	global_store_dwordx4 v[134:135], v[154:157], off
	global_store_dwordx4 v[134:135], v[158:161], off offset:128
	v_lshl_add_u64 v[134:135], v[134:135], 0, s[14:15]
	v_add_u32_e32 v167, 0x9000, v166
	global_load_dwordx4 v[228:231], v167, s[22:23]
	global_load_dwordx4 v[232:235], v167, s[22:23] offset:64
	global_load_dwordx4 v[236:239], v167, s[24:25]
	global_load_dwordx4 v[240:243], v167, s[24:25] offset:64
	v_pk_mul_f32 v[50:51], v[50:51], v[142:143] op_sel_hi:[1,0]
	v_pk_mul_f32 v[52:53], v[52:53], v[142:143] op_sel_hi:[1,0]
	v_pk_mul_f32 v[54:55], v[54:55], v[142:143] op_sel_hi:[1,0]
	v_pk_mul_f32 v[56:57], v[56:57], v[142:143] op_sel_hi:[1,0]
	v_pk_mul_f32 v[62:63], v[62:63], v[142:143] op_sel_hi:[1,0]
	v_pk_mul_f32 v[64:65], v[64:65], v[142:143] op_sel_hi:[1,0]
	v_pk_mul_f32 v[58:59], v[58:59], v[142:143] op_sel_hi:[1,0]
	v_pk_mul_f32 v[60:61], v[60:61], v[142:143] op_sel_hi:[1,0]
	s_waitcnt vmcnt(6)
; #define GPTR(T, ptr) ((__attribute__((address_space(1))) T*)(ptr))
; template <int EPI>
; __device__ __forceinline__ void gemm_tile(const GemmArgs& g, int brow, int bcol, int parity, bool first, bool nvalid, int nbrow, int nbcol) {
;     ...
;       _Pragma("unroll") for (int ai = 0; ai < 2; ++ai) _Pragma("unroll") for (int mh = 0; mh < 2; ++mh) {
;         SCHED;
;         _Pragma("unroll") for (int mm = 0; mm < 2; ++mm) _Pragma("unroll") for (int j = 0; j < 4; ++j) {
;           const int m = mh * 2 + mm;
;           const float rs = rstd_s[lrow0 + ai * HALF + m * 16 + fq * 4 + j] * qs;
;           _Pragma("unroll") for (int n = 0; n < 2; ++n) {
;             Wa[(mm * 16 + fq * 4 + j) * 36 + n * 16 + fr] = acc[ai][0][m][n][j] * rs;
;             Wb[(mm * 16 + fq * 4 + j) * 36 + n * 16 + fr] = acc[ai][1][m][n][j] * rs;
;           }
;         }
;         f32x4 cv[2][2], sv[2][2];
;         _Pragma("unroll") for (int ps = 0; ps < 2; ++ps) {
;           const int t = (wrow0 + ai * HALF + mh * 32 + ps * 16 + (lane >> 2)) & (TSEQ - 1);
;           const int dcol = dd0 + (lane & 3) * 8;
;           cv[ps][0] = *GPTR(const f32x4, g.rope + t * 64 + dcol); cv[ps][1] = *GPTR(const f32x4, g.rope + t * 64 + dcol + 4);
;           sv[ps][0] = *GPTR(const f32x4, g.rope + TSEQ * 64 + t * 64 + dcol); sv[ps][1] = *GPTR(const f32x4, g.rope + TSEQ * 64 + t * 64 + dcol + 4);
;         }
;         _Pragma("unroll") for (int ps = 0; ps < 2; ++ps) {
;           const int r_ = ps * 16 + (lane >> 2), c_ = (lane & 3) * 8;
;           const int grow = wrow0 + ai * HALF + mh * 32 + r_;
;           const float4 xa0 = *(const float4*)(Wa + r_ * 36 + c_), xa1 = *(const float4*)(Wa + r_ * 36 + c_ + 4);
;           const float4 xb0 = *(const float4*)(Wb + r_ * 36 + c_), xb1 = *(const float4*)(Wb + r_ * 36 + c_ + 4);
;           const f32x4 c0v = cv[ps][0], c1v = cv[ps][1], s0v = sv[ps][0], s1v = sv[ps][1];
;           u32x4 y1, y2;
;           y1[0] = pack2(xa0.x * c0v[0] - xb0.x * s0v[0], xa0.y * c0v[1] - xb0.y * s0v[1]);
;           y1[1] = pack2(xa0.z * c0v[2] - xb0.z * s0v[2], xa0.w * c0v[3] - xb0.w * s0v[3]);
;           y1[2] = pack2(xa1.x * c1v[0] - xb1.x * s1v[0], xa1.y * c1v[1] - xb1.y * s1v[1]);
;           y1[3] = pack2(xa1.z * c1v[2] - xb1.z * s1v[2], xa1.w * c1v[3] - xb1.w * s1v[3]);
;           y2[0] = pack2(xa0.x * s0v[0] + xb0.x * c0v[0], xa0.y * s0v[1] + xb0.y * c0v[1]);
	v_pk_mul_f32 v[162:163], v[62:63], v[178:179]
	v_pk_mul_f32 v[164:165], v[62:63], v[170:171]
	v_pk_fma_f32 v[62:63], v[50:51], v[178:179], v[164:165]
	v_pk_fma_f32 v[50:51], v[50:51], v[170:171], v[162:163] neg_lo:[0,0,1] neg_hi:[0,0,1]
	v_pk_mul_f32 v[162:163], v[64:65], v[180:181]
	v_pk_mul_f32 v[164:165], v[64:65], v[172:173]
	v_pk_fma_f32 v[64:65], v[52:53], v[180:181], v[164:165]
	v_pk_fma_f32 v[52:53], v[52:53], v[172:173], v[162:163] neg_lo:[0,0,1] neg_hi:[0,0,1]
	v_pk_mul_f32 v[162:163], v[58:59], v[182:183]
	v_pk_mul_f32 v[164:165], v[58:59], v[174:175]
	v_pk_fma_f32 v[58:59], v[54:55], v[182:183], v[164:165]
	v_pk_fma_f32 v[54:55], v[54:55], v[174:175], v[162:163] neg_lo:[0,0,1] neg_hi:[0,0,1]
	v_pk_mul_f32 v[162:163], v[60:61], v[184:185]
	v_pk_mul_f32 v[164:165], v[60:61], v[176:177]
	v_pk_fma_f32 v[60:61], v[56:57], v[184:185], v[164:165]
	v_pk_fma_f32 v[56:57], v[56:57], v[176:177], v[162:163] neg_lo:[0,0,1] neg_hi:[0,0,1]
	v_cvt_pk_bf16_f32 v146, v50, v51
	v_cvt_pk_bf16_f32 v147, v52, v53
	v_cvt_pk_bf16_f32 v148, v54, v55
	v_cvt_pk_bf16_f32 v149, v56, v57
	v_cvt_pk_bf16_f32 v150, v62, v63
	v_cvt_pk_bf16_f32 v151, v64, v65
	v_cvt_pk_bf16_f32 v152, v58, v59
	v_cvt_pk_bf16_f32 v153, v60, v61
	s_nop 1
	v_permlane16_swap_b32_e32 v146, v148
	v_permlane16_swap_b32_e32 v147, v149
	v_permlane16_swap_b32_e32 v150, v152
	v_permlane16_swap_b32_e32 v151, v153
	global_store_dwordx4 v[134:135], v[146:149], off
	global_store_dwordx4 v[134:135], v[150:153], off offset:128
	v_lshl_add_u64 v[134:135], v[134:135], 0, s[12:13]
	v_add_u32_e32 v167, 0xa000, v166
	global_load_dwordx4 v[170:173], v167, s[22:23]
	global_load_dwordx4 v[174:177], v167, s[22:23] offset:64
	global_load_dwordx4 v[178:181], v167, s[24:25]
	global_load_dwordx4 v[182:185], v167, s[24:25] offset:64
	v_pk_mul_f32 v[34:35], v[34:35], v[142:143] op_sel:[0,1] op_sel_hi:[1,1]
	v_pk_mul_f32 v[36:37], v[36:37], v[142:143] op_sel:[0,1] op_sel_hi:[1,1]
	v_pk_mul_f32 v[38:39], v[38:39], v[142:143] op_sel:[0,1] op_sel_hi:[1,1]
	v_pk_mul_f32 v[40:41], v[40:41], v[142:143] op_sel:[0,1] op_sel_hi:[1,1]
	v_pk_mul_f32 v[46:47], v[46:47], v[142:143] op_sel:[0,1] op_sel_hi:[1,1]
	v_pk_mul_f32 v[48:49], v[48:49], v[142:143] op_sel:[0,1] op_sel_hi:[1,1]
	v_pk_mul_f32 v[42:43], v[42:43], v[142:143] op_sel:[0,1] op_sel_hi:[1,1]
	v_pk_mul_f32 v[44:45], v[44:45], v[142:143] op_sel:[0,1] op_sel_hi:[1,1]
	s_waitcnt vmcnt(6)
	v_pk_mul_f32 v[162:163], v[46:47], v[236:237]
	v_pk_mul_f32 v[164:165], v[46:47], v[228:229]
	v_pk_fma_f32 v[46:47], v[34:35], v[236:237], v[164:165]
	v_pk_fma_f32 v[34:35], v[34:35], v[228:229], v[162:163] neg_lo:[0,0,1] neg_hi:[0,0,1]
	v_pk_mul_f32 v[162:163], v[48:49], v[238:239]
	v_pk_mul_f32 v[164:165], v[48:49], v[230:231]
	v_pk_fma_f32 v[48:49], v[36:37], v[238:239], v[164:165]
	v_pk_fma_f32 v[36:37], v[36:37], v[230:231], v[162:163] neg_lo:[0,0,1] neg_hi:[0,0,1]
	v_pk_mul_f32 v[162:163], v[42:43], v[240:241]
	v_pk_mul_f32 v[164:165], v[42:43], v[232:233]
	v_pk_fma_f32 v[42:43], v[38:39], v[240:241], v[164:165]
	v_pk_fma_f32 v[38:39], v[38:39], v[232:233], v[162:163] neg_lo:[0,0,1] neg_hi:[0,0,1]
	v_pk_mul_f32 v[162:163], v[44:45], v[242:243]
	v_pk_mul_f32 v[164:165], v[44:45], v[234:235]
	v_pk_fma_f32 v[44:45], v[40:41], v[242:243], v[164:165]
	v_pk_fma_f32 v[40:41], v[40:41], v[234:235], v[162:163] neg_lo:[0,0,1] neg_hi:[0,0,1]
	v_cvt_pk_bf16_f32 v154, v34, v35
	v_cvt_pk_bf16_f32 v155, v36, v37
	v_cvt_pk_bf16_f32 v156, v38, v39
	v_cvt_pk_bf16_f32 v157, v40, v41
	v_cvt_pk_bf16_f32 v158, v46, v47
	v_cvt_pk_bf16_f32 v159, v48, v49
	v_cvt_pk_bf16_f32 v160, v42, v43
	v_cvt_pk_bf16_f32 v161, v44, v45
	s_nop 1
	v_permlane16_swap_b32_e32 v154, v156
	v_permlane16_swap_b32_e32 v155, v157
	v_permlane16_swap_b32_e32 v158, v160
	v_permlane16_swap_b32_e32 v159, v161
	global_store_dwordx4 v[134:135], v[154:157], off
	global_store_dwordx4 v[134:135], v[158:161], off offset:128
	v_lshl_add_u64 v[134:135], v[134:135], 0, s[12:13]
	v_add_u32_e32 v167, 0xb000, v166
	global_load_dwordx4 v[228:231], v167, s[22:23]
	global_load_dwordx4 v[232:235], v167, s[22:23] offset:64
	global_load_dwordx4 v[236:239], v167, s[24:25]
	global_load_dwordx4 v[240:243], v167, s[24:25] offset:64
	v_pk_mul_f32 v[18:19], v[18:19], v[144:145] op_sel_hi:[1,0]
	v_pk_mul_f32 v[20:21], v[20:21], v[144:145] op_sel_hi:[1,0]
	v_pk_mul_f32 v[22:23], v[22:23], v[144:145] op_sel_hi:[1,0]
	v_pk_mul_f32 v[24:25], v[24:25], v[144:145] op_sel_hi:[1,0]
	v_pk_mul_f32 v[30:31], v[30:31], v[144:145] op_sel_hi:[1,0]
	v_pk_mul_f32 v[32:33], v[32:33], v[144:145] op_sel_hi:[1,0]
	v_pk_mul_f32 v[26:27], v[26:27], v[144:145] op_sel_hi:[1,0]
	v_pk_mul_f32 v[28:29], v[28:29], v[144:145] op_sel_hi:[1,0]
	s_waitcnt vmcnt(6)
; #define GPTR(T, ptr) ((__attribute__((address_space(1))) T*)(ptr))
; template <int EPI>
; __device__ __forceinline__ void gemm_tile(const GemmArgs& g, int brow, int bcol, int parity, bool first, bool nvalid, int nbrow, int nbcol) {
;     ...
;       _Pragma("unroll") for (int ai = 0; ai < 2; ++ai) _Pragma("unroll") for (int mh = 0; mh < 2; ++mh) {
;         SCHED;
;         _Pragma("unroll") for (int mm = 0; mm < 2; ++mm) _Pragma("unroll") for (int j = 0; j < 4; ++j) {
;           const int m = mh * 2 + mm;
;           const float rs = rstd_s[lrow0 + ai * HALF + m * 16 + fq * 4 + j] * qs;
;           _Pragma("unroll") for (int n = 0; n < 2; ++n) {
;             Wa[(mm * 16 + fq * 4 + j) * 36 + n * 16 + fr] = acc[ai][0][m][n][j] * rs;
;             Wb[(mm * 16 + fq * 4 + j) * 36 + n * 16 + fr] = acc[ai][1][m][n][j] * rs;
;           }
;         }
;         f32x4 cv[2][2], sv[2][2];
;         _Pragma("unroll") for (int ps = 0; ps < 2; ++ps) {
;           const int t = (wrow0 + ai * HALF + mh * 32 + ps * 16 + (lane >> 2)) & (TSEQ - 1);
;           const int dcol = dd0 + (lane & 3) * 8;
;           cv[ps][0] = *GPTR(const f32x4, g.rope + t * 64 + dcol); cv[ps][1] = *GPTR(const f32x4, g.rope + t * 64 + dcol + 4);
;           sv[ps][0] = *GPTR(const f32x4, g.rope + TSEQ * 64 + t * 64 + dcol); sv[ps][1] = *GPTR(const f32x4, g.rope + TSEQ * 64 + t * 64 + dcol + 4);
;         }
;         _Pragma("unroll") for (int ps = 0; ps < 2; ++ps) {
;           const int r_ = ps * 16 + (lane >> 2), c_ = (lane & 3) * 8;
;           const int grow = wrow0 + ai * HALF + mh * 32 + r_;
;           const float4 xa0 = *(const float4*)(Wa + r_ * 36 + c_), xa1 = *(const float4*)(Wa + r_ * 36 + c_ + 4);
;           const float4 xb0 = *(const float4*)(Wb + r_ * 36 + c_), xb1 = *(const float4*)(Wb + r_ * 36 + c_ + 4);
;           const f32x4 c0v = cv[ps][0], c1v = cv[ps][1], s0v = sv[ps][0], s1v = sv[ps][1];
;           u32x4 y1, y2;
;           y1[0] = pack2(xa0.x * c0v[0] - xb0.x * s0v[0], xa0.y * c0v[1] - xb0.y * s0v[1]);
;           y1[1] = pack2(xa0.z * c0v[2] - xb0.z * s0v[2], xa0.w * c0v[3] - xb0.w * s0v[3]);
;           y1[2] = pack2(xa1.x * c1v[0] - xb1.x * s1v[0], xa1.y * c1v[1] - xb1.y * s1v[1]);
;           y1[3] = pack2(xa1.z * c1v[2] - xb1.z * s1v[2], xa1.w * c1v[3] - xb1.w * s1v[3]);
;           y2[0] = pack2(xa0.x * s0v[0] + xb0.x * c0v[0], xa0.y * s0v[1] + xb0.y * c0v[1]);
	v_pk_mul_f32 v[162:163], v[30:31], v[178:179]
	v_pk_mul_f32 v[164:165], v[30:31], v[170:171]
	v_pk_fma_f32 v[30:31], v[18:19], v[178:179], v[164:165]
	v_pk_fma_f32 v[18:19], v[18:19], v[170:171], v[162:163] neg_lo:[0,0,1] neg_hi:[0,0,1]
	v_pk_mul_f32 v[162:163], v[32:33], v[180:181]
	v_pk_mul_f32 v[164:165], v[32:33], v[172:173]
	v_pk_fma_f32 v[32:33], v[20:21], v[180:181], v[164:165]
	v_pk_fma_f32 v[20:21], v[20:21], v[172:173], v[162:163] neg_lo:[0,0,1] neg_hi:[0,0,1]
	v_pk_mul_f32 v[162:163], v[26:27], v[182:183]
	v_pk_mul_f32 v[164:165], v[26:27], v[174:175]
	v_pk_fma_f32 v[26:27], v[22:23], v[182:183], v[164:165]
	v_pk_fma_f32 v[22:23], v[22:23], v[174:175], v[162:163] neg_lo:[0,0,1] neg_hi:[0,0,1]
	v_pk_mul_f32 v[162:163], v[28:29], v[184:185]
	v_pk_mul_f32 v[164:165], v[28:29], v[176:177]
	v_pk_fma_f32 v[28:29], v[24:25], v[184:185], v[164:165]
	v_pk_fma_f32 v[24:25], v[24:25], v[176:177], v[162:163] neg_lo:[0,0,1] neg_hi:[0,0,1]
	v_cvt_pk_bf16_f32 v146, v18, v19
	v_cvt_pk_bf16_f32 v147, v20, v21
	v_cvt_pk_bf16_f32 v148, v22, v23
	v_cvt_pk_bf16_f32 v149, v24, v25
	v_cvt_pk_bf16_f32 v150, v30, v31
	v_cvt_pk_bf16_f32 v151, v32, v33
	v_cvt_pk_bf16_f32 v152, v26, v27
	v_cvt_pk_bf16_f32 v153, v28, v29
	s_nop 1
	v_permlane16_swap_b32_e32 v146, v148
	v_permlane16_swap_b32_e32 v147, v149
	v_permlane16_swap_b32_e32 v150, v152
	v_permlane16_swap_b32_e32 v151, v153
	global_store_dwordx4 v[134:135], v[146:149], off
	global_store_dwordx4 v[134:135], v[150:153], off offset:128
	v_lshl_add_u64 v[134:135], v[134:135], 0, s[12:13]
	v_pk_mul_f32 v[2:3], v[2:3], v[144:145] op_sel:[0,1] op_sel_hi:[1,1]
	v_pk_mul_f32 v[4:5], v[4:5], v[144:145] op_sel:[0,1] op_sel_hi:[1,1]
	v_pk_mul_f32 v[6:7], v[6:7], v[144:145] op_sel:[0,1] op_sel_hi:[1,1]
	v_pk_mul_f32 v[8:9], v[8:9], v[144:145] op_sel:[0,1] op_sel_hi:[1,1]
	v_pk_mul_f32 v[14:15], v[14:15], v[144:145] op_sel:[0,1] op_sel_hi:[1,1]
	v_pk_mul_f32 v[16:17], v[16:17], v[144:145] op_sel:[0,1] op_sel_hi:[1,1]
	v_pk_mul_f32 v[10:11], v[10:11], v[144:145] op_sel:[0,1] op_sel_hi:[1,1]
	v_pk_mul_f32 v[12:13], v[12:13], v[144:145] op_sel:[0,1] op_sel_hi:[1,1]
	s_waitcnt vmcnt(2)
	v_pk_mul_f32 v[162:163], v[14:15], v[236:237]
	v_pk_mul_f32 v[164:165], v[14:15], v[228:229]
	v_pk_fma_f32 v[14:15], v[2:3], v[236:237], v[164:165]
	v_pk_fma_f32 v[2:3], v[2:3], v[228:229], v[162:163] neg_lo:[0,0,1] neg_hi:[0,0,1]
	v_pk_mul_f32 v[162:163], v[16:17], v[238:239]
	v_pk_mul_f32 v[164:165], v[16:17], v[230:231]
	v_pk_fma_f32 v[16:17], v[4:5], v[238:239], v[164:165]
	v_pk_fma_f32 v[4:5], v[4:5], v[230:231], v[162:163] neg_lo:[0,0,1] neg_hi:[0,0,1]
	v_pk_mul_f32 v[162:163], v[10:11], v[240:241]
	v_pk_mul_f32 v[164:165], v[10:11], v[232:233]
	v_pk_fma_f32 v[10:11], v[6:7], v[240:241], v[164:165]
	v_pk_fma_f32 v[6:7], v[6:7], v[232:233], v[162:163] neg_lo:[0,0,1] neg_hi:[0,0,1]
	v_pk_mul_f32 v[162:163], v[12:13], v[242:243]
	v_pk_mul_f32 v[164:165], v[12:13], v[234:235]
	v_pk_fma_f32 v[12:13], v[8:9], v[242:243], v[164:165]
	v_pk_fma_f32 v[8:9], v[8:9], v[234:235], v[162:163] neg_lo:[0,0,1] neg_hi:[0,0,1]
	v_cvt_pk_bf16_f32 v154, v2, v3
	v_cvt_pk_bf16_f32 v155, v4, v5
	v_cvt_pk_bf16_f32 v156, v6, v7
	v_cvt_pk_bf16_f32 v157, v8, v9
	v_cvt_pk_bf16_f32 v158, v14, v15
	v_cvt_pk_bf16_f32 v159, v16, v17
	v_cvt_pk_bf16_f32 v160, v10, v11
	v_cvt_pk_bf16_f32 v161, v12, v13
	s_nop 1
	v_permlane16_swap_b32_e32 v154, v156
	v_permlane16_swap_b32_e32 v155, v157
	v_permlane16_swap_b32_e32 v158, v160
	v_permlane16_swap_b32_e32 v159, v161
	global_store_dwordx4 v[134:135], v[154:157], off
	global_store_dwordx4 v[134:135], v[158:161], off offset:128
.Lswa_epi_done:
	s_mov_b64 s[12:13], -1
	s_and_b64 vcc, exec, s[0:1]
	s_branch .Lswa_epi_latch
